# NSA sel/window loops: bias-table LDS reads of each half-tile hoisted above its QK MFMAs (10 of 12 halves)
# speedup vs baseline: 1.0113x; 1.0113x over previous
; template <int MODE>
; __device__ __forceinline__ void nsa_compute(int cur, int buf, int t, int hl, u64 mymask, const bf16x8 (&Qf)[2][2], f32x4 (&O)[4][2], float (&m)[2], float (&l)[2],
;                                             const float (&inv)[2], float* impw, char* lds) {
;     ...
;   for (int s2 = 0; s2 < 2; ++s2) {
;     f32x4 S[2][2] = {};
;     bf16x8 kfr[2][2];
; #pragma unroll
;     for (int ks = 0; ks < 2; ++ks)
; #pragma unroll
;       for (int kk = 0; kk < 2; ++kk) kfr[ks][kk] = *(const bf16x8*)(kt + (32 * s2 + 16 * kk + fr) * 128 + (((ks * 4 + fq) ^ (fr & 7)) << 4));
;     __builtin_amdgcn_s_setprio(1);
; #pragma unroll
;     for (int ks = 0; ks < 2; ++ks)
; #pragma unroll
;       for (int kk = 0; kk < 2; ++kk)
; #pragma unroll
;         for (int r = 0; r < 2; ++r) S[kk][r] = mfma16(kfr[ks][kk], Qf[r][ks], S[kk][r]);
;     __builtin_amdgcn_s_setprio(0);
;     bf16x8 Pf[2];
;     float g1s[2] = {0.f, 0.f}, p3s[2] = {0.f, 0.f};
; #pragma unroll
;     for (int r = 0; r < 2; ++r) {
;       float sv[2][4];
; #pragma unroll
;       for (int kk = 0; kk < 2; ++kk)
; #pragma unroll
;         for (int e = 0; e < 4; ++e) {
;           const int off = 32 * s2 + 16 * kk + e;
;           int idx;
;           if (MODE <= 1) { idx = base - 16 * off; idx = idx > 0 ? idx : 0; } else idx = base - off;
;           sv[kk][e] = S[kk][r][e] * (0.125f * LOG2E) + tb[r * TS + idx];
;         }
;       float pv[2][4];
;       if (MODE == 1) {
; #pragma unroll
;         for (int kk = 0; kk < 2; ++kk)
; #pragma unroll
;           for (int e = 0; e < 4; ++e) pv[kk][e] = __builtin_amdgcn_exp2f(sv[kk][e] - m[r]) * inv[r];
; #pragma unroll
;         for (int kk = 0; kk < 2; ++kk) { g1s[kk] += pv[kk][0] + pv[kk][1] + pv[kk][2] + 0.5f * pv[kk][3]; p3s[kk] += 0.5f * pv[kk][3]; }
;       } else {
;         const float mxa = fmaxf(fmaxf(sv[0][0], sv[0][1]), sv[0][2]), mxb = fmaxf(fmaxf(sv[0][3], sv[1][0]), sv[1][1]);
;         float mx = fmaxf(fmaxf(fmaxf(sv[1][2], sv[1][3]), mxa), mxb);
;         if (MODE == 2) mx = selok ? mx : -__builtin_inff();
;         if (__any(mx > m[r] + 8.0f)) {
;           mx = fmaxf(mx, __shfl_xor(mx, 16)); mx = fmaxf(mx, __shfl_xor(mx, 32));
;           const float mn = fmaxf(m[r], mx), al = __builtin_amdgcn_exp2f(m[r] - mn);
;           m[r] = mn; l[r] *= al;
;           if (MODE != 0) {
; #pragma unroll
.LBB0_361:
	v_mov_b32 v72, v179
	s_lshl_b32 s64, s46, 13
	v_lshrrev_b32_e32 v73, 4, v72
	v_bfe_u32 v80, v72, 4, 2
	v_and_b32_e32 v81, 7, v72
	v_and_b32_e32 v92, 15, v72
	v_lshlrev_b32_e32 v93, 2, v80
	v_bitop3_b32 v72, v73, v81, 3 bitop3:0x6c
	v_bitop3_b32 v80, v80, v81, 4 bitop3:0x36
	v_lshlrev_b32_e32 v90, 7, v92
	v_lshl_or_b32 v91, v72, 4, s64
	v_lshl_or_b32 v100, v80, 4, s64
	v_or_b32_e32 v76, v91, v90
	v_or_b32_e32 v84, v100, v90
	ds_read_b128 v[72:75], v76
	ds_read_b128 v[76:79], v76 offset:2048
	ds_read_b128 v[80:83], v84
	ds_read_b128 v[84:87], v84 offset:2048
	s_mov_b32 s17, s74
	s_mov_b32 s74, s73
	v_sub_u32_e32 v251, v180, v93
	v_lshl_add_u32 v251, v251, 2, v235
	s_lshl_b32 s17, s17, 8
	v_subrev_u32_e32 v250, s17, v251
	v_add_u32_e32 v249, 0xa00, v250
	ds_read2_b32 v[98:99], v250 offset0:63 offset1:64
	ds_read2_b32 v[102:103], v250 offset0:61 offset1:62
	ds_read2_b32 v[168:169], v250 offset0:47 offset1:48
	ds_read2_b32 v[170:171], v250 offset0:45 offset1:46
	ds_read2_b32 v[172:173], v249 offset0:63 offset1:64
	ds_read2_b32 v[174:175], v249 offset0:61 offset1:62
	ds_read2_b32 v[194:195], v249 offset0:47 offset1:48
	ds_read2_b32 v[198:199], v249 offset0:45 offset1:46
	s_setprio 1
	s_waitcnt lgkmcnt(11)
	v_mfma_f32_16x16x32_bf16 v[94:97], v[72:75], v[0:3], 0
	v_mfma_f32_16x16x32_bf16 v[72:75], v[72:75], v[8:11], 0
	s_waitcnt lgkmcnt(10)
	v_mfma_f32_16x16x32_bf16 v[140:143], v[76:79], v[8:11], 0
	v_mfma_f32_16x16x32_bf16 v[136:139], v[76:79], v[0:3], 0
	s_waitcnt lgkmcnt(9)
	v_mfma_f32_16x16x32_bf16 v[94:97], v[80:83], v[4:7], v[94:97]
	v_mfma_f32_16x16x32_bf16 v[76:79], v[80:83], v[12:15], v[72:75]
	s_waitcnt lgkmcnt(8)
	v_mfma_f32_16x16x32_bf16 v[72:75], v[84:87], v[12:15], v[140:143]
	v_mfma_f32_16x16x32_bf16 v[144:147], v[84:87], v[4:7], v[136:139]
	s_setprio 0
	v_sub_u32_e32 v80, v180, v93
	v_lshl_add_u32 v80, v80, 2, v235
	v_subrev_u32_e32 v136, s17, v80
	s_waitcnt lgkmcnt(7)
	v_fmamk_f32 v94, v94, 0x3e38aa3b, v99
	v_fmamk_f32 v86, v95, 0x3e38aa3b, v98
	s_waitcnt lgkmcnt(6)
	v_fmamk_f32 v87, v96, 0x3e38aa3b, v103
	v_fmamk_f32 v84, v97, 0x3e38aa3b, v102
	s_waitcnt lgkmcnt(5)
	v_fmamk_f32 v81, v144, 0x3e38aa3b, v169
	v_fmamk_f32 v80, v145, 0x3e38aa3b, v168
	s_waitcnt lgkmcnt(4)
	v_fmamk_f32 v83, v146, 0x3e38aa3b, v171
	v_fmamk_f32 v82, v147, 0x3e38aa3b, v170
	v_max3_f32 v85, v94, v86, v87
	v_max3_f32 v88, v84, v81, v80
	v_max_f32_e32 v89, v83, v82
	v_max3_f32 v85, v89, v85, v88
	v_add_f32_e32 v88, 0x41000000, v192
	v_cmp_gt_f32_e32 vcc, v85, v88
	s_cbranch_vccz .LBB0_363
	ds_bpermute_b32 v88, v233, v85
	v_max_f32_e32 v85, v85, v85
	v_mov_b32_e32 v89, v193
	s_waitcnt lgkmcnt(0)
	v_max_f32_e32 v88, v88, v88
	v_max_f32_e32 v85, v85, v88
	ds_bpermute_b32 v88, v234, v85
	s_waitcnt lgkmcnt(0)
	v_max3_f32 v88, v192, v85, v88
	v_sub_f32_e32 v85, v192, v88
	v_exp_f32_e32 v96, v85
	v_mov_b64_e32 v[192:193], v[88:89]
	v_mul_f32_e32 v190, v190, v96
	v_pk_mul_f32 v[118:119], v[118:119], v[96:97] op_sel_hi:[1,0]
	v_pk_mul_f32 v[116:117], v[116:117], v[96:97] op_sel_hi:[1,0]
	v_pk_mul_f32 v[126:127], v[126:127], v[96:97] op_sel_hi:[1,0]
	v_pk_mul_f32 v[124:125], v[124:125], v[96:97] op_sel_hi:[1,0]
	v_pk_mul_f32 v[130:131], v[130:131], v[96:97] op_sel_hi:[1,0]
	v_pk_mul_f32 v[128:129], v[128:129], v[96:97] op_sel_hi:[1,0]
	v_pk_mul_f32 v[134:135], v[134:135], v[96:97] op_sel_hi:[1,0]
	v_pk_mul_f32 v[132:133], v[132:133], v[96:97] op_sel_hi:[1,0]
	s_branch .LBB0_364

; template <int MODE>
; __device__ __forceinline__ void nsa_compute(int cur, int buf, int t, int hl, u64 mymask, const bf16x8 (&Qf)[2][2], f32x4 (&O)[4][2], float (&m)[2], float (&l)[2],
;                                             const float (&inv)[2], float* impw, char* lds) {
;     ...
;     for (int r = 0; r < 2; ++r) {
;       float sv[2][4];
; #pragma unroll
;       for (int kk = 0; kk < 2; ++kk)
; #pragma unroll
;         for (int e = 0; e < 4; ++e) {
;           const int off = 32 * s2 + 16 * kk + e;
;           int idx;
;           if (MODE <= 1) { idx = base - 16 * off; idx = idx > 0 ? idx : 0; } else idx = base - off;
;           sv[kk][e] = S[kk][r][e] * (0.125f * LOG2E) + tb[r * TS + idx];
;         }
;       float pv[2][4];
;       if (MODE == 1) {
; #pragma unroll
;         for (int kk = 0; kk < 2; ++kk)
; #pragma unroll
;           for (int e = 0; e < 4; ++e) pv[kk][e] = __builtin_amdgcn_exp2f(sv[kk][e] - m[r]) * inv[r];
; #pragma unroll
;         for (int kk = 0; kk < 2; ++kk) { g1s[kk] += pv[kk][0] + pv[kk][1] + pv[kk][2] + 0.5f * pv[kk][3]; p3s[kk] += 0.5f * pv[kk][3]; }
;       } else {
;         const float mxa = fmaxf(fmaxf(sv[0][0], sv[0][1]), sv[0][2]), mxb = fmaxf(fmaxf(sv[0][3], sv[1][0]), sv[1][1]);
;         float mx = fmaxf(fmaxf(fmaxf(sv[1][2], sv[1][3]), mxa), mxb);
;         if (MODE == 2) mx = selok ? mx : -__builtin_inff();
;         if (__any(mx > m[r] + 8.0f)) {
;           mx = fmaxf(mx, __shfl_xor(mx, 16)); mx = fmaxf(mx, __shfl_xor(mx, 32));
;           const float mn = fmaxf(m[r], mx), al = __builtin_amdgcn_exp2f(m[r] - mn);
;           m[r] = mn; l[r] *= al;
;     ...
;         const float me = (MODE == 2) ? (selok ? m[r] : __builtin_inff()) : m[r];
;         float ps = 0.f;
; #pragma unroll
;         for (int kk = 0; kk < 2; ++kk)
; #pragma unroll
;           for (int e = 0; e < 4; ++e) { pv[kk][e] = __builtin_amdgcn_exp2f(sv[kk][e] - me); ps += pv[kk][e]; }
;         l[r] += ps;
;       }
.LBB0_364:
	v_sub_f32_e32 v85, v94, v88
	v_exp_f32_e32 v85, v85
	v_sub_f32_e32 v86, v86, v88
	v_exp_f32_e32 v86, v86
	v_sub_f32_e32 v87, v87, v88
	v_exp_f32_e32 v87, v87
	v_sub_f32_e32 v84, v84, v88
	v_exp_f32_e32 v84, v84
	v_add_f32_e32 v89, 0, v85
	v_add_f32_e32 v89, v86, v89
	v_add_f32_e32 v89, v87, v89
	v_sub_f32_e32 v81, v81, v88
	v_add_f32_e32 v94, v84, v89
	v_exp_f32_e32 v89, v81
	v_sub_f32_e32 v80, v80, v88
	v_add_f32_e32 v81, v89, v94
	v_exp_f32_e32 v94, v80
	s_nop 0
	v_add_f32_e32 v80, v94, v81
	v_sub_f32_e32 v81, v83, v88
	v_exp_f32_e32 v95, v81
	v_sub_f32_e32 v81, v82, v88
	v_exp_f32_e32 v88, v81
	v_add_f32_e32 v80, v95, v80
	v_add_f32_e32 v80, v88, v80
	v_add_f32_e32 v190, v190, v80
	s_waitcnt lgkmcnt(3)
	v_fmamk_f32 v81, v76, 0x3e38aa3b, v173
	v_fmamk_f32 v80, v77, 0x3e38aa3b, v172
	s_waitcnt lgkmcnt(2)
	v_fmamk_f32 v78, v78, 0x3e38aa3b, v175
	v_fmamk_f32 v82, v79, 0x3e38aa3b, v174
	s_waitcnt lgkmcnt(1)
	v_fmamk_f32 v77, v72, 0x3e38aa3b, v195
	v_fmamk_f32 v76, v73, 0x3e38aa3b, v194
	s_waitcnt lgkmcnt(0)
	v_fmamk_f32 v73, v74, 0x3e38aa3b, v199
	v_fmamk_f32 v72, v75, 0x3e38aa3b, v198
	v_max3_f32 v74, v81, v80, v78
	v_max3_f32 v75, v82, v77, v76
	v_max_f32_e32 v79, v73, v72
	v_max3_f32 v74, v79, v74, v75
	v_add_f32_e32 v75, 0x41000000, v193
	v_cmp_gt_f32_e32 vcc, v74, v75
	s_cbranch_vccz .LBB0_366
	ds_bpermute_b32 v75, v233, v74
	v_max_f32_e32 v74, v74, v74
	s_waitcnt lgkmcnt(0)
	v_max_f32_e32 v75, v75, v75
	v_max_f32_e32 v74, v74, v75
	ds_bpermute_b32 v75, v234, v74
	s_waitcnt lgkmcnt(0)
	v_max3_f32 v74, v193, v74, v75
	v_sub_f32_e32 v75, v193, v74
	v_exp_f32_e32 v96, v75
	v_mov_b32_e32 v193, v74
	v_mul_f32_e32 v191, v191, v96
	v_pk_mul_f32 v[106:107], v[106:107], v[96:97] op_sel_hi:[1,0]
	v_pk_mul_f32 v[104:105], v[104:105], v[96:97] op_sel_hi:[1,0]
	v_pk_mul_f32 v[110:111], v[110:111], v[96:97] op_sel_hi:[1,0]
	v_pk_mul_f32 v[108:109], v[108:109], v[96:97] op_sel_hi:[1,0]
	v_pk_mul_f32 v[114:115], v[114:115], v[96:97] op_sel_hi:[1,0]
	v_pk_mul_f32 v[112:113], v[112:113], v[96:97] op_sel_hi:[1,0]
	v_pk_mul_f32 v[122:123], v[122:123], v[96:97] op_sel_hi:[1,0]
	v_pk_mul_f32 v[120:121], v[120:121], v[96:97] op_sel_hi:[1,0]
	s_branch .LBB0_367

; template <int MODE>
; __device__ __forceinline__ void nsa_compute(int cur, int buf, int t, int hl, u64 mymask, const bf16x8 (&Qf)[2][2], f32x4 (&O)[4][2], float (&m)[2], float (&l)[2],
;                                             const float (&inv)[2], float* impw, char* lds) {
;     ...
;   for (int s2 = 0; s2 < 2; ++s2) {
;     f32x4 S[2][2] = {};
;     bf16x8 kfr[2][2];
; #pragma unroll
;     for (int ks = 0; ks < 2; ++ks)
; #pragma unroll
;       for (int kk = 0; kk < 2; ++kk) kfr[ks][kk] = *(const bf16x8*)(kt + (32 * s2 + 16 * kk + fr) * 128 + (((ks * 4 + fq) ^ (fr & 7)) << 4));
;     __builtin_amdgcn_s_setprio(1);
; #pragma unroll
;     for (int ks = 0; ks < 2; ++ks)
; #pragma unroll
;       for (int kk = 0; kk < 2; ++kk)
; #pragma unroll
;         for (int r = 0; r < 2; ++r) S[kk][r] = mfma16(kfr[ks][kk], Qf[r][ks], S[kk][r]);
;     __builtin_amdgcn_s_setprio(0);
;     bf16x8 Pf[2];
;     float g1s[2] = {0.f, 0.f}, p3s[2] = {0.f, 0.f};
; #pragma unroll
;     for (int r = 0; r < 2; ++r) {
;       float sv[2][4];
; #pragma unroll
;     ...
;         const float me = (MODE == 2) ? (selok ? m[r] : __builtin_inff()) : m[r];
;         float ps = 0.f;
; #pragma unroll
;         for (int kk = 0; kk < 2; ++kk)
; #pragma unroll
;           for (int e = 0; e < 4; ++e) { pv[kk][e] = __builtin_amdgcn_exp2f(sv[kk][e] - me); ps += pv[kk][e]; }
;         l[r] += ps;
;       }
;       if (MODE != 0) {
;         const unsigned w0 = pk2(pv[0][0], pv[0][1]), w1 = pk2(pv[0][2], pv[0][3]), w2 = pk2(pv[1][0], pv[1][1]), w3 = pk2(pv[1][2], pv[1][3]);
;         u32x4 pw; pw.x = w0; pw.y = w1; pw.z = w2; pw.w = w3;
;         Pf[r] = __builtin_bit_cast(bf16x8, pw);
;       }
;     }
;     if (MODE != 0) {
;       bf16x8 vfr[4];
; #pragma unroll
;       for (int df = 0; df < 4; ++df) {
;         const bf16x4 va = *(const bf16x4*)(vt + (df * 16 + fr) * 68 + 32 * s2 + 4 * fq);
;         const bf16x4 vb = *(const bf16x4*)(vt + (df * 16 + fr) * 68 + 32 * s2 + 16 + 4 * fq);
;         bf16x8 vf; vf[0] = va[0]; vf[1] = va[1]; vf[2] = va[2]; vf[3] = va[3]; vf[4] = vb[0]; vf[5] = vb[1]; vf[6] = vb[2]; vf[7] = vb[3];
;         vfr[df] = vf;
;       }
;       __builtin_amdgcn_s_setprio(1);
; #pragma unroll
;       for (int df = 0; df < 4; ++df)
; #pragma unroll
;         for (int r = 0; r < 2; ++r) O[df][r] = mfma16(vfr[df], Pf[r], O[df][r]);
;       __builtin_amdgcn_s_setprio(0);
.LBB0_367:
	v_sub_f32_e32 v75, v81, v74
	v_exp_f32_e32 v75, v75
	v_sub_f32_e32 v80, v80, v74
	v_exp_f32_e32 v80, v80
	v_sub_f32_e32 v78, v78, v74
	v_exp_f32_e32 v78, v78
	v_sub_f32_e32 v81, v82, v74
	v_exp_f32_e32 v81, v81
	v_sub_f32_e32 v77, v77, v74
	v_add_f32_e32 v79, 0, v75
	v_exp_f32_e32 v77, v77
	v_sub_f32_e32 v76, v76, v74
	v_add_f32_e32 v79, v80, v79
	v_exp_f32_e32 v76, v76
	v_sub_f32_e32 v73, v73, v74
	v_add_f32_e32 v79, v78, v79
	v_exp_f32_e32 v73, v73
	v_sub_f32_e32 v72, v72, v74
	v_add_f32_e32 v79, v81, v79
	v_exp_f32_e32 v72, v72
	v_add_f32_e32 v79, v77, v79
	v_add_f32_e32 v79, v76, v79
	v_add_f32_e32 v79, v73, v79
	s_lshl_b32 s17, s46, 9
	v_add_f32_e32 v74, v72, v79
	v_cvt_pk_bf16_f32 v149, v73, v72
	v_mul_u32_u24_e32 v72, 0x44, v92
	s_add_i32 s43, s64, s17
	v_lshlrev_b32_e32 v72, 1, v72
	v_lshlrev_b32_e32 v73, 1, v93
	v_cvt_pk_bf16_f32 v146, v75, v80
	v_add3_u32 v80, s43, v72, v73
	v_add_u32_e32 v137, 0x4000, v80
	v_add_u32_e32 v138, 0x4800, v80
	v_add_f32_e32 v191, v191, v74
	v_cvt_pk_bf16_f32 v147, v78, v81
	v_cvt_pk_bf16_f32 v148, v77, v76
	ds_read2_b64 v[72:75], v137 offset1:4
	ds_read2_b64 v[76:79], v138 offset0:16 offset1:20
	v_add_u32_e32 v139, 0x5000, v80
	v_add_u32_e32 v140, 0x5800, v80
	ds_read2_b64 v[150:153], v139 offset0:32 offset1:36
	ds_read2_b64 v[154:157], v140 offset0:48 offset1:52
	v_cvt_pk_bf16_f32 v142, v85, v86
	v_cvt_pk_bf16_f32 v143, v87, v84
	v_cvt_pk_bf16_f32 v144, v89, v94
	v_cvt_pk_bf16_f32 v145, v95, v88
	s_setprio 1
	s_waitcnt lgkmcnt(3)
	v_mfma_f32_16x16x32_bf16 v[84:87], v[72:75], v[142:145], v[116:119]
	v_mfma_f32_16x16x32_bf16 v[96:99], v[72:75], v[146:149], v[104:107]
	s_waitcnt lgkmcnt(2)
	v_mfma_f32_16x16x32_bf16 v[80:83], v[76:79], v[142:145], v[124:127]
	v_mfma_f32_16x16x32_bf16 v[92:95], v[76:79], v[146:149], v[108:111]
	s_waitcnt lgkmcnt(1)
	v_mfma_f32_16x16x32_bf16 v[76:79], v[150:153], v[142:145], v[128:131]
	v_mfma_f32_16x16x32_bf16 v[108:111], v[150:153], v[146:149], v[112:115]
	s_waitcnt lgkmcnt(0)
	v_mfma_f32_16x16x32_bf16 v[72:75], v[154:157], v[142:145], v[132:135]
	v_mfma_f32_16x16x32_bf16 v[104:107], v[154:157], v[146:149], v[120:123]
	s_setprio 0
	v_add_u32_e32 v88, v91, v90
	v_add_u32_e32 v100, v100, v90
	ds_read_b128 v[112:115], v88 offset:4096
	ds_read_b128 v[116:119], v88 offset:6144
	ds_read_b128 v[88:91], v100 offset:4096
	ds_read_b128 v[120:123], v100 offset:6144
	v_add_u32_e32 v251, 0xa00, v136
	ds_read2_b32 v[168:169], v136 offset0:31 offset1:32
	ds_read2_b32 v[170:171], v136 offset0:29 offset1:30
	ds_read2_b32 v[172:173], v136 offset0:15 offset1:16
	ds_read2_b32 v[174:175], v136 offset0:13 offset1:14
	ds_read2_b32 v[198:199], v251 offset0:31 offset1:32
	ds_read2_b32 v[200:201], v251 offset0:29 offset1:30
	ds_read2_b32 v[202:203], v251 offset0:15 offset1:16
	ds_read2_b32 v[204:205], v251 offset0:13 offset1:14
	s_setprio 1
	s_waitcnt lgkmcnt(11)
	v_mfma_f32_16x16x32_bf16 v[100:103], v[112:115], v[0:3], 0
	v_mfma_f32_16x16x32_bf16 v[112:115], v[112:115], v[8:11], 0
	s_waitcnt lgkmcnt(10)
	v_mfma_f32_16x16x32_bf16 v[124:127], v[116:119], v[0:3], 0
	v_mfma_f32_16x16x32_bf16 v[116:119], v[116:119], v[8:11], 0
	s_waitcnt lgkmcnt(9)
	v_mfma_f32_16x16x32_bf16 v[128:131], v[88:91], v[4:7], v[100:103]
	v_mfma_f32_16x16x32_bf16 v[100:103], v[88:91], v[12:15], v[112:115]
	s_waitcnt lgkmcnt(8)
	v_mfma_f32_16x16x32_bf16 v[88:91], v[120:123], v[12:15], v[116:119]
	v_mfma_f32_16x16x32_bf16 v[124:127], v[120:123], v[4:7], v[124:127]
	s_setprio 0
	s_nop 0
	s_waitcnt lgkmcnt(7)
	s_nop 0
	v_fmamk_f32 v123, v128, 0x3e38aa3b, v169
	v_fmamk_f32 v118, v129, 0x3e38aa3b, v168
	s_waitcnt lgkmcnt(6)
	v_fmamk_f32 v122, v130, 0x3e38aa3b, v171
	v_fmamk_f32 v116, v131, 0x3e38aa3b, v170
	s_waitcnt lgkmcnt(5)
	v_fmamk_f32 v119, v124, 0x3e38aa3b, v173
	v_fmamk_f32 v114, v125, 0x3e38aa3b, v172
	s_waitcnt lgkmcnt(4)
	v_fmamk_f32 v113, v126, 0x3e38aa3b, v175
	v_fmamk_f32 v112, v127, 0x3e38aa3b, v174
	v_max3_f32 v115, v123, v118, v122
	v_max3_f32 v117, v116, v119, v114
	v_max_f32_e32 v120, v113, v112
	v_max3_f32 v115, v120, v115, v117
	v_add_f32_e32 v117, 0x41000000, v192
	v_cmp_gt_f32_e32 vcc, v115, v117
	s_cbranch_vccz .LBB0_369
	ds_bpermute_b32 v117, v233, v115
	v_max_f32_e32 v115, v115, v115
	v_mov_b32_e32 v121, v193
	s_waitcnt lgkmcnt(0)
	v_max_f32_e32 v117, v117, v117
	v_max_f32_e32 v115, v115, v117
	ds_bpermute_b32 v117, v234, v115
	s_waitcnt lgkmcnt(0)
	v_max3_f32 v120, v192, v115, v117
	v_sub_f32_e32 v115, v192, v120
	v_exp_f32_e32 v124, v115
	v_mov_b64_e32 v[192:193], v[120:121]
	v_mul_f32_e32 v190, v190, v124
	v_pk_mul_f32 v[86:87], v[86:87], v[124:125] op_sel_hi:[1,0]
	v_pk_mul_f32 v[84:85], v[84:85], v[124:125] op_sel_hi:[1,0]
	v_pk_mul_f32 v[82:83], v[82:83], v[124:125] op_sel_hi:[1,0]
	v_pk_mul_f32 v[80:81], v[80:81], v[124:125] op_sel_hi:[1,0]
	v_pk_mul_f32 v[78:79], v[78:79], v[124:125] op_sel_hi:[1,0]
	v_pk_mul_f32 v[76:77], v[76:77], v[124:125] op_sel_hi:[1,0]
	v_pk_mul_f32 v[74:75], v[74:75], v[124:125] op_sel_hi:[1,0]
	v_pk_mul_f32 v[72:73], v[72:73], v[124:125] op_sel_hi:[1,0]
	s_branch .LBB0_370

; template <int MODE>
; __device__ __forceinline__ void nsa_compute(int cur, int buf, int t, int hl, u64 mymask, const bf16x8 (&Qf)[2][2], f32x4 (&O)[4][2], float (&m)[2], float (&l)[2],
;                                             const float (&inv)[2], float* impw, char* lds) {
;     ...
;     for (int r = 0; r < 2; ++r) {
;       float sv[2][4];
; #pragma unroll
;       for (int kk = 0; kk < 2; ++kk)
; #pragma unroll
;         for (int e = 0; e < 4; ++e) {
;           const int off = 32 * s2 + 16 * kk + e;
;           int idx;
;           if (MODE <= 1) { idx = base - 16 * off; idx = idx > 0 ? idx : 0; } else idx = base - off;
;           sv[kk][e] = S[kk][r][e] * (0.125f * LOG2E) + tb[r * TS + idx];
;         }
;       float pv[2][4];
;       if (MODE == 1) {
; #pragma unroll
;         for (int kk = 0; kk < 2; ++kk)
; #pragma unroll
;           for (int e = 0; e < 4; ++e) pv[kk][e] = __builtin_amdgcn_exp2f(sv[kk][e] - m[r]) * inv[r];
; #pragma unroll
;         for (int kk = 0; kk < 2; ++kk) { g1s[kk] += pv[kk][0] + pv[kk][1] + pv[kk][2] + 0.5f * pv[kk][3]; p3s[kk] += 0.5f * pv[kk][3]; }
;       } else {
;         const float mxa = fmaxf(fmaxf(sv[0][0], sv[0][1]), sv[0][2]), mxb = fmaxf(fmaxf(sv[0][3], sv[1][0]), sv[1][1]);
;         float mx = fmaxf(fmaxf(fmaxf(sv[1][2], sv[1][3]), mxa), mxb);
;         if (MODE == 2) mx = selok ? mx : -__builtin_inff();
;         if (__any(mx > m[r] + 8.0f)) {
;           mx = fmaxf(mx, __shfl_xor(mx, 16)); mx = fmaxf(mx, __shfl_xor(mx, 32));
;           const float mn = fmaxf(m[r], mx), al = __builtin_amdgcn_exp2f(m[r] - mn);
;           m[r] = mn; l[r] *= al;
;     ...
;         const float me = (MODE == 2) ? (selok ? m[r] : __builtin_inff()) : m[r];
;         float ps = 0.f;
; #pragma unroll
;         for (int kk = 0; kk < 2; ++kk)
; #pragma unroll
;           for (int e = 0; e < 4; ++e) { pv[kk][e] = __builtin_amdgcn_exp2f(sv[kk][e] - me); ps += pv[kk][e]; }
;         l[r] += ps;
;       }
.LBB0_370:
	v_sub_f32_e32 v115, v123, v120
	v_exp_f32_e32 v115, v115
	v_sub_f32_e32 v117, v118, v120
	v_exp_f32_e32 v117, v117
	v_sub_f32_e32 v118, v122, v120
	v_exp_f32_e32 v118, v118
	v_sub_f32_e32 v116, v116, v120
	v_exp_f32_e32 v116, v116
	v_sub_f32_e32 v119, v119, v120
	v_add_f32_e32 v121, 0, v115
	v_exp_f32_e32 v119, v119
	v_sub_f32_e32 v114, v114, v120
	v_add_f32_e32 v121, v117, v121
	v_exp_f32_e32 v114, v114
	v_add_f32_e32 v121, v118, v121
	v_add_f32_e32 v121, v116, v121
	v_add_f32_e32 v121, v119, v121
	v_sub_f32_e32 v113, v113, v120
	v_add_f32_e32 v122, v114, v121
	v_exp_f32_e32 v121, v113
	v_sub_f32_e32 v112, v112, v120
	v_exp_f32_e32 v120, v112
	v_add_f32_e32 v113, v121, v122
	v_add_f32_e32 v112, v120, v113
	v_add_f32_e32 v190, v190, v112
	s_waitcnt lgkmcnt(3)
	v_fmamk_f32 v113, v100, 0x3e38aa3b, v199
	v_fmamk_f32 v112, v101, 0x3e38aa3b, v198
	s_waitcnt lgkmcnt(2)
	v_fmamk_f32 v101, v102, 0x3e38aa3b, v201
	v_fmamk_f32 v100, v103, 0x3e38aa3b, v200
	s_waitcnt lgkmcnt(1)
	v_fmamk_f32 v103, v88, 0x3e38aa3b, v203
	v_fmamk_f32 v102, v89, 0x3e38aa3b, v202
	s_waitcnt lgkmcnt(0)
	v_fmamk_f32 v89, v90, 0x3e38aa3b, v205
	v_fmamk_f32 v88, v91, 0x3e38aa3b, v204
	v_max3_f32 v90, v113, v112, v101
	v_max3_f32 v91, v100, v103, v102
	v_max_f32_e32 v122, v89, v88
	v_max3_f32 v90, v122, v90, v91
	v_add_f32_e32 v91, 0x41000000, v193
	v_cmp_gt_f32_e32 vcc, v90, v91
	s_cbranch_vccz .LBB0_372
	ds_bpermute_b32 v91, v233, v90
	v_max_f32_e32 v90, v90, v90
	s_waitcnt lgkmcnt(0)
	v_max_f32_e32 v91, v91, v91
	v_max_f32_e32 v90, v90, v91
	ds_bpermute_b32 v91, v234, v90
	s_waitcnt lgkmcnt(0)
	v_max3_f32 v90, v193, v90, v91
	v_sub_f32_e32 v91, v193, v90
	v_exp_f32_e32 v122, v91
	v_mov_b32_e32 v193, v90
	v_mul_f32_e32 v191, v191, v122
	v_pk_mul_f32 v[98:99], v[98:99], v[122:123] op_sel_hi:[1,0]
	v_pk_mul_f32 v[96:97], v[96:97], v[122:123] op_sel_hi:[1,0]
	v_pk_mul_f32 v[94:95], v[94:95], v[122:123] op_sel_hi:[1,0]
	v_pk_mul_f32 v[92:93], v[92:93], v[122:123] op_sel_hi:[1,0]
	v_pk_mul_f32 v[110:111], v[110:111], v[122:123] op_sel_hi:[1,0]
	v_pk_mul_f32 v[108:109], v[108:109], v[122:123] op_sel_hi:[1,0]
	v_pk_mul_f32 v[106:107], v[106:107], v[122:123] op_sel_hi:[1,0]
	v_pk_mul_f32 v[104:105], v[104:105], v[122:123] op_sel_hi:[1,0]
	v_mov_b64_e32 v[194:195], v[190:191]
	s_branch .LBB0_373

; template <int MODE>
; __device__ __forceinline__ void nsa_compute(int cur, int buf, int t, int hl, u64 mymask, const bf16x8 (&Qf)[2][2], f32x4 (&O)[4][2], float (&m)[2], float (&l)[2],
;                                             const float (&inv)[2], float* impw, char* lds) {
;     ...
;   for (int s2 = 0; s2 < 2; ++s2) {
;     f32x4 S[2][2] = {};
;     bf16x8 kfr[2][2];
; #pragma unroll
;     for (int ks = 0; ks < 2; ++ks)
; #pragma unroll
;       for (int kk = 0; kk < 2; ++kk) kfr[ks][kk] = *(const bf16x8*)(kt + (32 * s2 + 16 * kk + fr) * 128 + (((ks * 4 + fq) ^ (fr & 7)) << 4));
;     __builtin_amdgcn_s_setprio(1);
; #pragma unroll
;     for (int ks = 0; ks < 2; ++ks)
; #pragma unroll
;       for (int kk = 0; kk < 2; ++kk)
; #pragma unroll
;         for (int r = 0; r < 2; ++r) S[kk][r] = mfma16(kfr[ks][kk], Qf[r][ks], S[kk][r]);
;     __builtin_amdgcn_s_setprio(0);
;     bf16x8 Pf[2];
;     float g1s[2] = {0.f, 0.f}, p3s[2] = {0.f, 0.f};
; #pragma unroll
;     for (int r = 0; r < 2; ++r) {
;       float sv[2][4];
; #pragma unroll
;       for (int kk = 0; kk < 2; ++kk)
; #pragma unroll
;         for (int e = 0; e < 4; ++e) {
;           const int off = 32 * s2 + 16 * kk + e;
;           int idx;
;           if (MODE <= 1) { idx = base - 16 * off; idx = idx > 0 ? idx : 0; } else idx = base - off;
;           sv[kk][e] = S[kk][r][e] * (0.125f * LOG2E) + tb[r * TS + idx];
;         }
;       float pv[2][4];
;       if (MODE == 1) {
; #pragma unroll
;         for (int kk = 0; kk < 2; ++kk)
; #pragma unroll
;           for (int e = 0; e < 4; ++e) pv[kk][e] = __builtin_amdgcn_exp2f(sv[kk][e] - m[r]) * inv[r];
; #pragma unroll
;         for (int kk = 0; kk < 2; ++kk) { g1s[kk] += pv[kk][0] + pv[kk][1] + pv[kk][2] + 0.5f * pv[kk][3]; p3s[kk] += 0.5f * pv[kk][3]; }
;       } else {
;         const float mxa = fmaxf(fmaxf(sv[0][0], sv[0][1]), sv[0][2]), mxb = fmaxf(fmaxf(sv[0][3], sv[1][0]), sv[1][1]);
;         float mx = fmaxf(fmaxf(fmaxf(sv[1][2], sv[1][3]), mxa), mxb);
;         if (MODE == 2) mx = selok ? mx : -__builtin_inff();
;     ...
;         const float me = (MODE == 2) ? (selok ? m[r] : __builtin_inff()) : m[r];
;         float ps = 0.f;
; #pragma unroll
;         for (int kk = 0; kk < 2; ++kk)
; #pragma unroll
;           for (int e = 0; e < 4; ++e) { pv[kk][e] = __builtin_amdgcn_exp2f(sv[kk][e] - me); ps += pv[kk][e]; }
;         l[r] += ps;
;       }
.LBB0_377:
	v_add_f32_e32 v104, 0, v113
	v_add_f32_e32 v104, v112, v104
	v_add_f32_e32 v104, v114, v104
	v_add_f32_e32 v104, v115, v104
	v_add_f32_e32 v104, v116, v104
	v_add_f32_e32 v104, v117, v104
	v_add_f32_e32 v104, v118, v104
	v_add_f32_e32 v104, v119, v104
	s_cmp_lt_i32 s16, 0
	v_add_f32_e32 v195, v195, v104
	s_cbranch_scc1 .LBB0_380
	v_mov_b32 v104, v179
	s_lshl_b32 s71, s46, 13
	v_lshrrev_b32_e32 v105, 4, v104
	v_bfe_u32 v120, v104, 4, 2
	v_and_b32_e32 v112, 7, v104
	v_and_b32_e32 v149, 15, v104
	v_bitop3_b32 v104, v105, v112, 3 bitop3:0x6c
	v_bitop3_b32 v112, v120, v112, 4 bitop3:0x36
	v_lshlrev_b32_e32 v146, 7, v149
	v_lshl_or_b32 v147, v104, 4, s71
	v_lshl_or_b32 v148, v112, 4, s71
	v_or_b32_e32 v108, v147, v146
	v_or_b32_e32 v116, v148, v146
	ds_read_b128 v[104:107], v108
	ds_read_b128 v[108:111], v108 offset:2048
	ds_read_b128 v[112:115], v116
	ds_read_b128 v[116:119], v116 offset:2048
	v_lshlrev_b32_e32 v150, 2, v120
	v_sub_u32_e32 v251, v180, v150
	v_lshl_add_u32 v251, v251, 2, v235
	s_lshl_b32 s16, s16, 8
	v_subrev_u32_e32 v250, s16, v251
	v_add_u32_e32 v249, 0xa00, v250
	ds_read2_b32 v[198:199], v250 offset0:63 offset1:64
	ds_read2_b32 v[200:201], v250 offset0:61 offset1:62
	ds_read2_b32 v[202:203], v250 offset0:47 offset1:48
	ds_read2_b32 v[204:205], v250 offset0:45 offset1:46
	ds_read2_b32 v[206:207], v249 offset0:63 offset1:64
	ds_read2_b32 v[208:209], v249 offset0:61 offset1:62
	ds_read2_b32 v[210:211], v249 offset0:47 offset1:48
	ds_read2_b32 v[236:237], v249 offset0:45 offset1:46
	s_setprio 1
	s_waitcnt lgkmcnt(11)
	v_mfma_f32_16x16x32_bf16 v[120:123], v[104:107], v[0:3], 0
	v_mfma_f32_16x16x32_bf16 v[104:107], v[104:107], v[8:11], 0
	s_waitcnt lgkmcnt(10)
	v_mfma_f32_16x16x32_bf16 v[128:131], v[108:111], v[0:3], 0
	v_mfma_f32_16x16x32_bf16 v[108:111], v[108:111], v[8:11], 0
	s_waitcnt lgkmcnt(9)
	v_mfma_f32_16x16x32_bf16 v[124:127], v[112:115], v[12:15], v[104:107]
	s_waitcnt lgkmcnt(8)
	v_mfma_f32_16x16x32_bf16 v[104:107], v[116:119], v[4:7], v[128:131]
	v_mfma_f32_16x16x32_bf16 v[116:119], v[116:119], v[12:15], v[108:111]
	v_mfma_f32_16x16x32_bf16 v[120:123], v[112:115], v[4:7], v[120:123]
	s_setprio 0
	s_nop 0
	v_sub_u32_e32 v108, v180, v150
	v_lshl_add_u32 v108, v108, 2, v235
	v_subrev_u32_e32 v154, s16, v108
	s_waitcnt lgkmcnt(7)
	s_nop 1
	v_fmamk_f32 v135, v120, 0x3e38aa3b, v199
	v_fmamk_f32 v134, v121, 0x3e38aa3b, v198
	s_waitcnt lgkmcnt(6)
	v_fmamk_f32 v133, v122, 0x3e38aa3b, v201
	v_fmamk_f32 v132, v123, 0x3e38aa3b, v200
	s_waitcnt lgkmcnt(5)
	v_fmamk_f32 v129, v104, 0x3e38aa3b, v203
	v_fmamk_f32 v128, v105, 0x3e38aa3b, v202
	s_waitcnt lgkmcnt(4)
	v_fmamk_f32 v131, v106, 0x3e38aa3b, v205
	v_fmamk_f32 v130, v107, 0x3e38aa3b, v204
	v_max3_f32 v104, v135, v134, v133
	v_max3_f32 v105, v132, v129, v128
	v_max_f32_e32 v106, v131, v130
	v_max3_f32 v104, v106, v104, v105
	v_add_f32_e32 v105, 0x41000000, v192
	v_cmp_gt_f32_e32 vcc, v104, v105
	s_cbranch_vccz .LBB0_381
	ds_bpermute_b32 v105, v233, v104
	v_max_f32_e32 v104, v104, v104
	v_mov_b32_e32 v137, v193
	v_mov_b32_e32 v197, v195
	s_waitcnt lgkmcnt(0)
	v_max_f32_e32 v105, v105, v105
	v_max_f32_e32 v104, v104, v105
	ds_bpermute_b32 v105, v234, v104
	s_waitcnt lgkmcnt(0)
	v_max3_f32 v136, v192, v104, v105
	v_sub_f32_e32 v104, v192, v136
	v_exp_f32_e32 v120, v104
	v_mov_b64_e32 v[192:193], v[136:137]
	v_mul_f32_e32 v196, v194, v120
	v_pk_mul_f32 v[114:115], v[90:91], v[120:121] op_sel_hi:[1,0]
	v_pk_mul_f32 v[112:113], v[88:89], v[120:121] op_sel_hi:[1,0]
	v_pk_mul_f32 v[106:107], v[102:103], v[120:121] op_sel_hi:[1,0]
	v_pk_mul_f32 v[104:105], v[100:101], v[120:121] op_sel_hi:[1,0]
	v_pk_mul_f32 v[110:111], v[94:95], v[120:121] op_sel_hi:[1,0]
	v_pk_mul_f32 v[108:109], v[92:93], v[120:121] op_sel_hi:[1,0]
	v_pk_mul_f32 v[122:123], v[82:83], v[120:121] op_sel_hi:[1,0]
	v_pk_mul_f32 v[120:121], v[80:81], v[120:121] op_sel_hi:[1,0]
	s_branch .LBB0_382

; template <int MODE>
; __device__ __forceinline__ void nsa_compute(int cur, int buf, int t, int hl, u64 mymask, const bf16x8 (&Qf)[2][2], f32x4 (&O)[4][2], float (&m)[2], float (&l)[2],
;                                             const float (&inv)[2], float* impw, char* lds) {
;     ...
;     for (int r = 0; r < 2; ++r) {
;       float sv[2][4];
; #pragma unroll
;       for (int kk = 0; kk < 2; ++kk)
; #pragma unroll
;         for (int e = 0; e < 4; ++e) {
;           const int off = 32 * s2 + 16 * kk + e;
;           int idx;
;           if (MODE <= 1) { idx = base - 16 * off; idx = idx > 0 ? idx : 0; } else idx = base - off;
;           sv[kk][e] = S[kk][r][e] * (0.125f * LOG2E) + tb[r * TS + idx];
;         }
;       float pv[2][4];
;       if (MODE == 1) {
; #pragma unroll
;         for (int kk = 0; kk < 2; ++kk)
; #pragma unroll
;           for (int e = 0; e < 4; ++e) pv[kk][e] = __builtin_amdgcn_exp2f(sv[kk][e] - m[r]) * inv[r];
; #pragma unroll
;         for (int kk = 0; kk < 2; ++kk) { g1s[kk] += pv[kk][0] + pv[kk][1] + pv[kk][2] + 0.5f * pv[kk][3]; p3s[kk] += 0.5f * pv[kk][3]; }
;       } else {
;         const float mxa = fmaxf(fmaxf(sv[0][0], sv[0][1]), sv[0][2]), mxb = fmaxf(fmaxf(sv[0][3], sv[1][0]), sv[1][1]);
;         float mx = fmaxf(fmaxf(fmaxf(sv[1][2], sv[1][3]), mxa), mxb);
;         if (MODE == 2) mx = selok ? mx : -__builtin_inff();
;         if (__any(mx > m[r] + 8.0f)) {
;           mx = fmaxf(mx, __shfl_xor(mx, 16)); mx = fmaxf(mx, __shfl_xor(mx, 32));
;           const float mn = fmaxf(m[r], mx), al = __builtin_amdgcn_exp2f(m[r] - mn);
;           m[r] = mn; l[r] *= al;
;     ...
;         const float me = (MODE == 2) ? (selok ? m[r] : __builtin_inff()) : m[r];
;         float ps = 0.f;
; #pragma unroll
;         for (int kk = 0; kk < 2; ++kk)
; #pragma unroll
;           for (int e = 0; e < 4; ++e) { pv[kk][e] = __builtin_amdgcn_exp2f(sv[kk][e] - me); ps += pv[kk][e]; }
;         l[r] += ps;
;       }
.LBB0_382:
	v_sub_f32_e32 v135, v135, v136
	v_exp_f32_e32 v151, v135
	v_sub_f32_e32 v134, v134, v136
	v_exp_f32_e32 v152, v134
	v_sub_f32_e32 v133, v133, v136
	v_exp_f32_e32 v153, v133
	v_sub_f32_e32 v132, v132, v136
	v_exp_f32_e32 v155, v132
	v_sub_f32_e32 v129, v129, v136
	v_add_f32_e32 v135, 0, v151
	v_exp_f32_e32 v156, v129
	v_sub_f32_e32 v128, v128, v136
	v_add_f32_e32 v134, v152, v135
	v_exp_f32_e32 v157, v128
	v_add_f32_e32 v133, v153, v134
	v_add_f32_e32 v132, v155, v133
	v_add_f32_e32 v129, v156, v132
	v_add_f32_e32 v128, v157, v129
	v_sub_f32_e32 v129, v131, v136
	v_exp_f32_e32 v158, v129
	v_sub_f32_e32 v129, v130, v136
	v_exp_f32_e32 v159, v129
	v_add_f32_e32 v128, v158, v128
	v_add_f32_e32 v128, v159, v128
	v_add_f32_e32 v196, v196, v128
	s_waitcnt lgkmcnt(3)
	v_fmamk_f32 v135, v124, 0x3e38aa3b, v207
	v_fmamk_f32 v134, v125, 0x3e38aa3b, v206
	s_waitcnt lgkmcnt(2)
	v_fmamk_f32 v145, v126, 0x3e38aa3b, v209
	v_fmamk_f32 v144, v127, 0x3e38aa3b, v208
	s_waitcnt lgkmcnt(1)
	v_fmamk_f32 v133, v116, 0x3e38aa3b, v211
	v_fmamk_f32 v132, v117, 0x3e38aa3b, v210
	s_waitcnt lgkmcnt(0)
	v_fmamk_f32 v117, v118, 0x3e38aa3b, v237
	v_fmamk_f32 v116, v119, 0x3e38aa3b, v236
	v_max3_f32 v118, v135, v134, v145
	v_max3_f32 v119, v144, v133, v132
	v_max_f32_e32 v124, v117, v116
	v_max3_f32 v118, v124, v118, v119
	v_add_f32_e32 v119, 0x41000000, v193
	v_cmp_gt_f32_e32 vcc, v118, v119
	s_cbranch_vccz .LBB0_384
	ds_bpermute_b32 v119, v233, v118
	v_max_f32_e32 v118, v118, v118
	s_waitcnt lgkmcnt(0)
	v_max_f32_e32 v119, v119, v119
	v_max_f32_e32 v118, v118, v119
	ds_bpermute_b32 v119, v234, v118
	s_waitcnt lgkmcnt(0)
	v_max3_f32 v118, v193, v118, v119
	v_sub_f32_e32 v119, v193, v118
	v_exp_f32_e32 v140, v119
	v_mov_b32_e32 v193, v118
	v_mul_f32_e32 v197, v197, v140
	v_pk_mul_f32 v[126:127], v[98:99], v[140:141] op_sel_hi:[1,0]
	v_pk_mul_f32 v[124:125], v[96:97], v[140:141] op_sel_hi:[1,0]
	v_pk_mul_f32 v[130:131], v[86:87], v[140:141] op_sel_hi:[1,0]
	v_pk_mul_f32 v[128:129], v[84:85], v[140:141] op_sel_hi:[1,0]
	v_pk_mul_f32 v[138:139], v[78:79], v[140:141] op_sel_hi:[1,0]
	v_pk_mul_f32 v[136:137], v[76:77], v[140:141] op_sel_hi:[1,0]
	v_pk_mul_f32 v[142:143], v[74:75], v[140:141] op_sel_hi:[1,0]
	v_pk_mul_f32 v[140:141], v[72:73], v[140:141] op_sel_hi:[1,0]
	s_branch .LBB0_385

; template <int MODE>
; __device__ __forceinline__ void nsa_compute(int cur, int buf, int t, int hl, u64 mymask, const bf16x8 (&Qf)[2][2], f32x4 (&O)[4][2], float (&m)[2], float (&l)[2],
;                                             const float (&inv)[2], float* impw, char* lds) {
;     ...
;   for (int s2 = 0; s2 < 2; ++s2) {
;     f32x4 S[2][2] = {};
;     bf16x8 kfr[2][2];
; #pragma unroll
;     for (int ks = 0; ks < 2; ++ks)
; #pragma unroll
;       for (int kk = 0; kk < 2; ++kk) kfr[ks][kk] = *(const bf16x8*)(kt + (32 * s2 + 16 * kk + fr) * 128 + (((ks * 4 + fq) ^ (fr & 7)) << 4));
;     __builtin_amdgcn_s_setprio(1);
; #pragma unroll
;     for (int ks = 0; ks < 2; ++ks)
; #pragma unroll
;       for (int kk = 0; kk < 2; ++kk)
; #pragma unroll
;         for (int r = 0; r < 2; ++r) S[kk][r] = mfma16(kfr[ks][kk], Qf[r][ks], S[kk][r]);
;     __builtin_amdgcn_s_setprio(0);
;     bf16x8 Pf[2];
;     float g1s[2] = {0.f, 0.f}, p3s[2] = {0.f, 0.f};
; #pragma unroll
;     for (int r = 0; r < 2; ++r) {
;       float sv[2][4];
; #pragma unroll
;     ...
;         const float me = (MODE == 2) ? (selok ? m[r] : __builtin_inff()) : m[r];
;         float ps = 0.f;
; #pragma unroll
;         for (int kk = 0; kk < 2; ++kk)
; #pragma unroll
;           for (int e = 0; e < 4; ++e) { pv[kk][e] = __builtin_amdgcn_exp2f(sv[kk][e] - me); ps += pv[kk][e]; }
;         l[r] += ps;
;       }
;       if (MODE != 0) {
;         const unsigned w0 = pk2(pv[0][0], pv[0][1]), w1 = pk2(pv[0][2], pv[0][3]), w2 = pk2(pv[1][0], pv[1][1]), w3 = pk2(pv[1][2], pv[1][3]);
;         u32x4 pw; pw.x = w0; pw.y = w1; pw.z = w2; pw.w = w3;
;         Pf[r] = __builtin_bit_cast(bf16x8, pw);
;       }
;     }
;     if (MODE != 0) {
;       bf16x8 vfr[4];
; #pragma unroll
;       for (int df = 0; df < 4; ++df) {
;         const bf16x4 va = *(const bf16x4*)(vt + (df * 16 + fr) * 68 + 32 * s2 + 4 * fq);
;         const bf16x4 vb = *(const bf16x4*)(vt + (df * 16 + fr) * 68 + 32 * s2 + 16 + 4 * fq);
;         bf16x8 vf; vf[0] = va[0]; vf[1] = va[1]; vf[2] = va[2]; vf[3] = va[3]; vf[4] = vb[0]; vf[5] = vb[1]; vf[6] = vb[2]; vf[7] = vb[3];
;         vfr[df] = vf;
;       }
;       __builtin_amdgcn_s_setprio(1);
; #pragma unroll
;       for (int df = 0; df < 4; ++df)
; #pragma unroll
;         for (int r = 0; r < 2; ++r) O[df][r] = mfma16(vfr[df], Pf[r], O[df][r]);
;       __builtin_amdgcn_s_setprio(0);
.LBB0_385:
	v_sub_f32_e32 v119, v135, v118
	v_exp_f32_e32 v119, v119
	v_sub_f32_e32 v134, v134, v118
	v_exp_f32_e32 v134, v134
	v_sub_f32_e32 v145, v145, v118
	v_exp_f32_e32 v145, v145
	v_sub_f32_e32 v144, v144, v118
	v_exp_f32_e32 v144, v144
	v_sub_f32_e32 v133, v133, v118
	v_add_f32_e32 v135, 0, v119
	v_exp_f32_e32 v133, v133
	v_sub_f32_e32 v132, v132, v118
	v_add_f32_e32 v135, v134, v135
	v_exp_f32_e32 v132, v132
	v_sub_f32_e32 v117, v117, v118
	v_add_f32_e32 v135, v145, v135
	v_exp_f32_e32 v117, v117
	v_sub_f32_e32 v116, v116, v118
	v_add_f32_e32 v135, v144, v135
	v_exp_f32_e32 v116, v116
	v_add_f32_e32 v135, v133, v135
	v_add_f32_e32 v135, v132, v135
	v_add_f32_e32 v135, v117, v135
	s_lshl_b32 s16, s46, 9
	v_add_f32_e32 v118, v116, v135
	v_cvt_pk_bf16_f32 v167, v117, v116
	v_mul_u32_u24_e32 v116, 0x44, v149
	s_add_i32 s72, s71, s16
	v_lshlrev_b32_e32 v116, 1, v116
	v_lshlrev_b32_e32 v117, 1, v150
	v_add3_u32 v116, s72, v116, v117
	v_cvt_pk_bf16_f32 v161, v153, v155
	v_cvt_pk_bf16_f32 v162, v156, v157
	v_add_u32_e32 v155, 0x4000, v116
	v_add_u32_e32 v156, 0x4800, v116
	v_cvt_pk_bf16_f32 v160, v151, v152
	v_cvt_pk_bf16_f32 v163, v158, v159
	v_cvt_pk_bf16_f32 v164, v119, v134
	v_cvt_pk_bf16_f32 v166, v133, v132
	ds_read2_b64 v[132:135], v155 offset1:4
	ds_read2_b64 v[150:153], v156 offset0:16 offset1:20
	v_add_u32_e32 v157, 0x5000, v116
	v_add_u32_e32 v158, 0x5800, v116
	ds_read2_b64 v[168:171], v157 offset0:32 offset1:36
	ds_read2_b64 v[172:175], v158 offset0:48 offset1:52
	v_add_f32_e32 v197, v197, v118
	v_cvt_pk_bf16_f32 v165, v145, v144
	s_setprio 1
	s_waitcnt lgkmcnt(3)
	v_mfma_f32_16x16x32_bf16 v[116:119], v[132:135], v[160:163], v[112:115]
	v_mfma_f32_16x16x32_bf16 v[132:135], v[132:135], v[164:167], v[124:127]
	s_waitcnt lgkmcnt(2)
	v_mfma_f32_16x16x32_bf16 v[112:115], v[150:153], v[160:163], v[104:107]
	v_mfma_f32_16x16x32_bf16 v[128:131], v[150:153], v[164:167], v[128:131]
	s_waitcnt lgkmcnt(1)
	v_mfma_f32_16x16x32_bf16 v[108:111], v[168:171], v[160:163], v[108:111]
	v_mfma_f32_16x16x32_bf16 v[124:127], v[168:171], v[164:167], v[136:139]
	s_waitcnt lgkmcnt(0)
	v_mfma_f32_16x16x32_bf16 v[104:107], v[172:175], v[160:163], v[120:123]
	v_mfma_f32_16x16x32_bf16 v[120:123], v[172:175], v[164:167], v[140:143]
	s_setprio 0
	s_nop 1
	v_add_u32_e32 v140, v147, v146
	v_add_u32_e32 v148, v148, v146
	ds_read_b128 v[136:139], v140 offset:4096
	ds_read_b128 v[140:143], v140 offset:6144
	ds_read_b128 v[144:147], v148 offset:4096
	ds_read_b128 v[148:151], v148 offset:6144
	v_add_u32_e32 v251, 0xa00, v154
	ds_read2_b32 v[202:203], v154 offset0:31 offset1:32
	ds_read2_b32 v[204:205], v154 offset0:29 offset1:30
	ds_read2_b32 v[206:207], v154 offset0:15 offset1:16
	ds_read2_b32 v[208:209], v154 offset0:13 offset1:14
	ds_read2_b32 v[210:211], v251 offset0:31 offset1:32
	ds_read2_b32 v[236:237], v251 offset0:29 offset1:30
	ds_read2_b32 v[238:239], v251 offset0:15 offset1:16
	ds_read2_b32 v[240:241], v251 offset0:13 offset1:14
	s_setprio 1
	s_waitcnt lgkmcnt(11)
	v_mfma_f32_16x16x32_bf16 v[160:163], v[136:139], v[0:3], 0
	v_mfma_f32_16x16x32_bf16 v[136:139], v[136:139], v[8:11], 0
	s_waitcnt lgkmcnt(10)
	v_mfma_f32_16x16x32_bf16 v[168:171], v[140:143], v[8:11], 0
	v_mfma_f32_16x16x32_bf16 v[164:167], v[140:143], v[0:3], 0
	s_waitcnt lgkmcnt(9)
	v_mfma_f32_16x16x32_bf16 v[160:163], v[144:147], v[4:7], v[160:163]
	v_mfma_f32_16x16x32_bf16 v[140:143], v[144:147], v[12:15], v[136:139]
	s_waitcnt lgkmcnt(8)
	v_mfma_f32_16x16x32_bf16 v[136:139], v[148:151], v[12:15], v[168:171]
	v_mfma_f32_16x16x32_bf16 v[164:167], v[148:151], v[4:7], v[164:167]
	s_setprio 0
	s_waitcnt lgkmcnt(7)
	s_nop 1
	v_fmamk_f32 v160, v160, 0x3e38aa3b, v203
	v_fmamk_f32 v150, v161, 0x3e38aa3b, v202
	s_waitcnt lgkmcnt(6)
	v_fmamk_f32 v159, v162, 0x3e38aa3b, v205
	v_fmamk_f32 v148, v163, 0x3e38aa3b, v204
	s_waitcnt lgkmcnt(5)
	v_fmamk_f32 v151, v164, 0x3e38aa3b, v207
	v_fmamk_f32 v146, v165, 0x3e38aa3b, v206
	s_waitcnt lgkmcnt(4)
	v_fmamk_f32 v145, v166, 0x3e38aa3b, v209
	v_fmamk_f32 v144, v167, 0x3e38aa3b, v208
	v_max3_f32 v147, v160, v150, v159
	v_max3_f32 v149, v148, v151, v146
	v_max_f32_e32 v152, v145, v144
	v_max3_f32 v147, v152, v147, v149
	v_add_f32_e32 v149, 0x41000000, v192
	v_cmp_gt_f32_e32 vcc, v147, v149
	s_cbranch_vccz .LBB0_387
	ds_bpermute_b32 v149, v233, v147
	v_max_f32_e32 v147, v147, v147
	v_mov_b32_e32 v153, v193
	s_waitcnt lgkmcnt(0)
	v_max_f32_e32 v149, v149, v149
	v_max_f32_e32 v147, v147, v149
	ds_bpermute_b32 v149, v234, v147
	s_waitcnt lgkmcnt(0)
	v_max3_f32 v152, v192, v147, v149
	v_sub_f32_e32 v147, v192, v152
	v_exp_f32_e32 v162, v147
	v_mov_b64_e32 v[192:193], v[152:153]
	v_mul_f32_e32 v196, v196, v162
	v_pk_mul_f32 v[118:119], v[118:119], v[162:163] op_sel_hi:[1,0]
	v_pk_mul_f32 v[116:117], v[116:117], v[162:163] op_sel_hi:[1,0]
	v_pk_mul_f32 v[114:115], v[114:115], v[162:163] op_sel_hi:[1,0]
	v_pk_mul_f32 v[112:113], v[112:113], v[162:163] op_sel_hi:[1,0]
	v_pk_mul_f32 v[110:111], v[110:111], v[162:163] op_sel_hi:[1,0]
	v_pk_mul_f32 v[108:109], v[108:109], v[162:163] op_sel_hi:[1,0]
	v_pk_mul_f32 v[106:107], v[106:107], v[162:163] op_sel_hi:[1,0]
	v_pk_mul_f32 v[104:105], v[104:105], v[162:163] op_sel_hi:[1,0]
	s_branch .LBB0_388

; template <int MODE>
; __device__ __forceinline__ void nsa_compute(int cur, int buf, int t, int hl, u64 mymask, const bf16x8 (&Qf)[2][2], f32x4 (&O)[4][2], float (&m)[2], float (&l)[2],
;                                             const float (&inv)[2], float* impw, char* lds) {
;     ...
;     for (int r = 0; r < 2; ++r) {
;       float sv[2][4];
; #pragma unroll
;       for (int kk = 0; kk < 2; ++kk)
; #pragma unroll
;         for (int e = 0; e < 4; ++e) {
;           const int off = 32 * s2 + 16 * kk + e;
;           int idx;
;           if (MODE <= 1) { idx = base - 16 * off; idx = idx > 0 ? idx : 0; } else idx = base - off;
;           sv[kk][e] = S[kk][r][e] * (0.125f * LOG2E) + tb[r * TS + idx];
;         }
;       float pv[2][4];
;       if (MODE == 1) {
; #pragma unroll
;         for (int kk = 0; kk < 2; ++kk)
; #pragma unroll
;           for (int e = 0; e < 4; ++e) pv[kk][e] = __builtin_amdgcn_exp2f(sv[kk][e] - m[r]) * inv[r];
; #pragma unroll
;         for (int kk = 0; kk < 2; ++kk) { g1s[kk] += pv[kk][0] + pv[kk][1] + pv[kk][2] + 0.5f * pv[kk][3]; p3s[kk] += 0.5f * pv[kk][3]; }
;       } else {
;         const float mxa = fmaxf(fmaxf(sv[0][0], sv[0][1]), sv[0][2]), mxb = fmaxf(fmaxf(sv[0][3], sv[1][0]), sv[1][1]);
;         float mx = fmaxf(fmaxf(fmaxf(sv[1][2], sv[1][3]), mxa), mxb);
;         if (MODE == 2) mx = selok ? mx : -__builtin_inff();
;         if (__any(mx > m[r] + 8.0f)) {
;           mx = fmaxf(mx, __shfl_xor(mx, 16)); mx = fmaxf(mx, __shfl_xor(mx, 32));
;           const float mn = fmaxf(m[r], mx), al = __builtin_amdgcn_exp2f(m[r] - mn);
;           m[r] = mn; l[r] *= al;
;     ...
;         const float me = (MODE == 2) ? (selok ? m[r] : __builtin_inff()) : m[r];
;         float ps = 0.f;
; #pragma unroll
;         for (int kk = 0; kk < 2; ++kk)
; #pragma unroll
;           for (int e = 0; e < 4; ++e) { pv[kk][e] = __builtin_amdgcn_exp2f(sv[kk][e] - me); ps += pv[kk][e]; }
;         l[r] += ps;
;       }
.LBB0_388:
	v_sub_f32_e32 v147, v160, v152
	v_exp_f32_e32 v147, v147
	v_sub_f32_e32 v149, v150, v152
	v_exp_f32_e32 v149, v149
	v_sub_f32_e32 v150, v159, v152
	v_exp_f32_e32 v150, v150
	v_sub_f32_e32 v148, v148, v152
	v_exp_f32_e32 v148, v148
	v_sub_f32_e32 v151, v151, v152
	v_add_f32_e32 v153, 0, v147
	v_exp_f32_e32 v151, v151
	v_sub_f32_e32 v146, v146, v152
	v_add_f32_e32 v153, v149, v153
	v_exp_f32_e32 v146, v146
	v_add_f32_e32 v153, v150, v153
	v_add_f32_e32 v153, v148, v153
	v_add_f32_e32 v153, v151, v153
	v_sub_f32_e32 v145, v145, v152
	v_add_f32_e32 v159, v146, v153
	v_exp_f32_e32 v153, v145
	v_sub_f32_e32 v144, v144, v152
	v_exp_f32_e32 v152, v144
	v_add_f32_e32 v145, v153, v159
	v_add_f32_e32 v144, v152, v145
	v_add_f32_e32 v196, v196, v144
	s_waitcnt lgkmcnt(3)
	v_fmamk_f32 v145, v140, 0x3e38aa3b, v211
	v_fmamk_f32 v144, v141, 0x3e38aa3b, v210
	s_waitcnt lgkmcnt(2)
	v_fmamk_f32 v141, v142, 0x3e38aa3b, v237
	v_fmamk_f32 v140, v143, 0x3e38aa3b, v236
	s_waitcnt lgkmcnt(1)
	v_fmamk_f32 v143, v136, 0x3e38aa3b, v239
	v_fmamk_f32 v142, v137, 0x3e38aa3b, v238
	s_waitcnt lgkmcnt(0)
	v_fmamk_f32 v137, v138, 0x3e38aa3b, v241
	v_fmamk_f32 v136, v139, 0x3e38aa3b, v240
	v_max3_f32 v138, v145, v144, v141
	v_max3_f32 v139, v140, v143, v142
	v_max_f32_e32 v154, v137, v136
	v_max3_f32 v138, v154, v138, v139
	v_add_f32_e32 v139, 0x41000000, v193
	v_cmp_gt_f32_e32 vcc, v138, v139
	s_cbranch_vccz .LBB0_390
	ds_bpermute_b32 v139, v233, v138
	v_max_f32_e32 v138, v138, v138
	s_waitcnt lgkmcnt(0)
	v_max_f32_e32 v139, v139, v139
	v_max_f32_e32 v138, v138, v139
	ds_bpermute_b32 v139, v234, v138
	s_waitcnt lgkmcnt(0)
	v_max3_f32 v138, v193, v138, v139
	v_sub_f32_e32 v139, v193, v138
	v_exp_f32_e32 v154, v139
	v_mov_b32_e32 v193, v138
	v_mul_f32_e32 v197, v197, v154
	v_pk_mul_f32 v[134:135], v[134:135], v[154:155] op_sel_hi:[1,0]
	v_pk_mul_f32 v[132:133], v[132:133], v[154:155] op_sel_hi:[1,0]
	v_pk_mul_f32 v[130:131], v[130:131], v[154:155] op_sel_hi:[1,0]
	v_pk_mul_f32 v[128:129], v[128:129], v[154:155] op_sel_hi:[1,0]
	v_pk_mul_f32 v[126:127], v[126:127], v[154:155] op_sel_hi:[1,0]
	v_pk_mul_f32 v[124:125], v[124:125], v[154:155] op_sel_hi:[1,0]
	v_pk_mul_f32 v[122:123], v[122:123], v[154:155] op_sel_hi:[1,0]
	v_pk_mul_f32 v[120:121], v[120:121], v[154:155] op_sel_hi:[1,0]
	s_branch .LBB0_391

; template <int MODE>
; __device__ __forceinline__ void nsa_compute(int cur, int buf, int t, int hl, u64 mymask, const bf16x8 (&Qf)[2][2], f32x4 (&O)[4][2], float (&m)[2], float (&l)[2],
;                                             const float (&inv)[2], float* impw, char* lds) {
;     ...
;   const bool selok = (MODE == 2) ? (((mymask >> cur) & 1ull) != 0ull) : true;
;   const float* tb = (MODE == 3) ? (const float*)(lds + NSA_TW) + hl * 640 : (const float*)(lds + NSA_T) + hl * 4160;
;   constexpr int TS = (MODE == 3) ? 640 : 4160;
;   const int base = (MODE <= 1) ? (t - 31 - 16 * (cur * 64 + 4 * fq) + 64) : (t - cur * 64 - 4 * fq + 64);
; #pragma unroll
;   for (int s2 = 0; s2 < 2; ++s2) {
;     f32x4 S[2][2] = {};
;     bf16x8 kfr[2][2];
; #pragma unroll
;     for (int ks = 0; ks < 2; ++ks)
; #pragma unroll
;       for (int kk = 0; kk < 2; ++kk) kfr[ks][kk] = *(const bf16x8*)(kt + (32 * s2 + 16 * kk + fr) * 128 + (((ks * 4 + fq) ^ (fr & 7)) << 4));
;     __builtin_amdgcn_s_setprio(1);
; #pragma unroll
;     for (int ks = 0; ks < 2; ++ks)
; #pragma unroll
;       for (int kk = 0; kk < 2; ++kk)
; #pragma unroll
;         for (int r = 0; r < 2; ++r) S[kk][r] = mfma16(kfr[ks][kk], Qf[r][ks], S[kk][r]);
;     __builtin_amdgcn_s_setprio(0);
;     bf16x8 Pf[2];
;     float g1s[2] = {0.f, 0.f}, p3s[2] = {0.f, 0.f};
; #pragma unroll
;     for (int r = 0; r < 2; ++r) {
;       float sv[2][4];
; #pragma unroll
;       for (int kk = 0; kk < 2; ++kk)
; #pragma unroll
;         for (int e = 0; e < 4; ++e) {
;           const int off = 32 * s2 + 16 * kk + e;
;           int idx;
;           if (MODE <= 1) { idx = base - 16 * off; idx = idx > 0 ? idx : 0; } else idx = base - off;
;           sv[kk][e] = S[kk][r][e] * (0.125f * LOG2E) + tb[r * TS + idx];
;         }
;       float pv[2][4];
;       if (MODE == 1) {
; #pragma unroll
;         for (int kk = 0; kk < 2; ++kk)
; #pragma unroll
;           for (int e = 0; e < 4; ++e) pv[kk][e] = __builtin_amdgcn_exp2f(sv[kk][e] - m[r]) * inv[r];
; #pragma unroll
;         for (int kk = 0; kk < 2; ++kk) { g1s[kk] += pv[kk][0] + pv[kk][1] + pv[kk][2] + 0.5f * pv[kk][3]; p3s[kk] += 0.5f * pv[kk][3]; }
;       } else {
;         const float mxa = fmaxf(fmaxf(sv[0][0], sv[0][1]), sv[0][2]), mxb = fmaxf(fmaxf(sv[0][3], sv[1][0]), sv[1][1]);
;         float mx = fmaxf(fmaxf(fmaxf(sv[1][2], sv[1][3]), mxa), mxb);
.LBB0_436:
	s_mov_b32 s17, s75
	s_lshl_b64 s[30:31], 1, s17
	v_mov_b32 v74, v179
	v_and_b32_e32 v73, s31, v187
	v_lshrrev_b32_e32 v75, 4, v74
	v_bfe_u32 v80, v74, 4, 2
	v_and_b32_e32 v72, s30, v186
	v_and_b32_e32 v81, 7, v74
	v_and_b32_e32 v94, 15, v74
	s_lshl_b32 s63, s74, 13
	v_cmp_eq_u64_e64 s[36:37], 0, v[72:73]
	v_lshlrev_b32_e32 v95, 2, v80
	v_bitop3_b32 v72, v75, v81, 3 bitop3:0x6c
	v_bitop3_b32 v80, v80, v81, 4 bitop3:0x36
	v_lshlrev_b32_e32 v91, 7, v94
	v_lshl_or_b32 v92, v72, 4, s63
	v_lshl_or_b32 v93, v80, 4, s63
	v_or_b32_e32 v76, v92, v91
	v_or_b32_e32 v84, v93, v91
	ds_read_b128 v[72:75], v76
	ds_read_b128 v[76:79], v76 offset:2048
	ds_read_b128 v[80:83], v84
	ds_read_b128 v[84:87], v84 offset:2048
	s_mov_b32 s75, s46
	v_sub_u32_e32 v251, v180, v95
	v_lshl_add_u32 v251, v251, 2, v181
	s_lshl_b32 s17, s17, 8
	v_subrev_u32_e32 v250, s17, v251
	v_add_u32_e32 v249, 0x8400, v250
	v_add_u32_e32 v248, 0xc500, v250
	ds_read2_b32 v[114:115], v249 offset0:63 offset1:64
	ds_read2_b32 v[116:117], v249 offset0:61 offset1:62
	ds_read2_b32 v[118:119], v249 offset0:47 offset1:48
	ds_read2_b32 v[138:139], v249 offset0:45 offset1:46
	ds_read2_b32 v[140:141], v248 offset0:63 offset1:64
	ds_read2_b32 v[142:143], v248 offset0:61 offset1:62
	ds_read2_b32 v[144:145], v248 offset0:47 offset1:48
	ds_read2_b32 v[148:149], v248 offset0:45 offset1:46
	s_setprio 1
	s_waitcnt lgkmcnt(11)
	v_mfma_f32_16x16x32_bf16 v[96:99], v[72:75], v[0:3], 0
	v_mfma_f32_16x16x32_bf16 v[72:75], v[72:75], v[8:11], 0
	s_waitcnt lgkmcnt(10)
	v_mfma_f32_16x16x32_bf16 v[104:107], v[76:79], v[8:11], 0
	v_mfma_f32_16x16x32_bf16 v[100:103], v[76:79], v[0:3], 0
	s_waitcnt lgkmcnt(9)
	v_mfma_f32_16x16x32_bf16 v[96:99], v[80:83], v[4:7], v[96:99]
	v_mfma_f32_16x16x32_bf16 v[76:79], v[80:83], v[12:15], v[72:75]
	s_waitcnt lgkmcnt(8)
	v_mfma_f32_16x16x32_bf16 v[72:75], v[84:87], v[12:15], v[104:107]
	v_mfma_f32_16x16x32_bf16 v[100:103], v[84:87], v[4:7], v[100:103]
	s_setprio 0
	v_sub_u32_e32 v80, v180, v95
	v_lshl_add_u32 v80, v80, 2, v181
	v_subrev_u32_e32 v90, s17, v80
	s_waitcnt lgkmcnt(7)
	v_fmamk_f32 v87, v96, 0x3e38aa3b, v115
	v_fmamk_f32 v86, v97, 0x3e38aa3b, v114
	s_waitcnt lgkmcnt(6)
	v_fmamk_f32 v83, v98, 0x3e38aa3b, v117
	v_fmamk_f32 v82, v99, 0x3e38aa3b, v116
	s_waitcnt lgkmcnt(5)
	v_fmamk_f32 v81, v100, 0x3e38aa3b, v119
	v_fmamk_f32 v80, v101, 0x3e38aa3b, v118
	s_waitcnt lgkmcnt(4)
	v_fmamk_f32 v97, v102, 0x3e38aa3b, v139
	v_fmamk_f32 v84, v103, 0x3e38aa3b, v138
	v_max3_f32 v85, v87, v86, v83
	v_max3_f32 v88, v82, v81, v80
	v_max_f32_e32 v89, v97, v84
	v_max3_f32 v85, v89, v85, v88
	v_cndmask_b32_e64 v85, v85, v225, s[36:37]
	v_add_f32_e32 v88, 0x41000000, v188
	v_cmp_gt_f32_e32 vcc, v85, v88
	s_cbranch_vccz .LBB0_438
	ds_bpermute_b32 v88, v233, v85
	v_max_f32_e32 v85, v85, v85
	v_mov_b32_e32 v89, v189
	s_waitcnt lgkmcnt(0)
	v_max_f32_e32 v88, v88, v88
	v_max_f32_e32 v85, v85, v88
	ds_bpermute_b32 v88, v234, v85
	s_waitcnt lgkmcnt(0)
	v_max3_f32 v88, v188, v85, v88
	v_sub_f32_e32 v85, v188, v88
	v_exp_f32_e32 v96, v85
	v_mov_b64_e32 v[188:189], v[88:89]
	v_mul_f32_e32 v190, v190, v96
	v_pk_mul_f32 v[18:19], v[18:19], v[96:97] op_sel_hi:[1,0]
	v_pk_mul_f32 v[16:17], v[16:17], v[96:97] op_sel_hi:[1,0]
	v_pk_mul_f32 v[26:27], v[26:27], v[96:97] op_sel_hi:[1,0]
	v_pk_mul_f32 v[24:25], v[24:25], v[96:97] op_sel_hi:[1,0]
	v_pk_mul_f32 v[34:35], v[34:35], v[96:97] op_sel_hi:[1,0]
	v_pk_mul_f32 v[32:33], v[32:33], v[96:97] op_sel_hi:[1,0]
	v_pk_mul_f32 v[42:43], v[42:43], v[96:97] op_sel_hi:[1,0]
	v_pk_mul_f32 v[40:41], v[40:41], v[96:97] op_sel_hi:[1,0]
	s_branch .LBB0_439

; template <int MODE>
; __device__ __forceinline__ void nsa_compute(int cur, int buf, int t, int hl, u64 mymask, const bf16x8 (&Qf)[2][2], f32x4 (&O)[4][2], float (&m)[2], float (&l)[2],
;                                             const float (&inv)[2], float* impw, char* lds) {
;     ...
;     for (int r = 0; r < 2; ++r) {
;       float sv[2][4];
; #pragma unroll
;       for (int kk = 0; kk < 2; ++kk)
; #pragma unroll
;         for (int e = 0; e < 4; ++e) {
;           const int off = 32 * s2 + 16 * kk + e;
;           int idx;
;           if (MODE <= 1) { idx = base - 16 * off; idx = idx > 0 ? idx : 0; } else idx = base - off;
;           sv[kk][e] = S[kk][r][e] * (0.125f * LOG2E) + tb[r * TS + idx];
;         }
;       float pv[2][4];
;       if (MODE == 1) {
; #pragma unroll
;         for (int kk = 0; kk < 2; ++kk)
; #pragma unroll
;           for (int e = 0; e < 4; ++e) pv[kk][e] = __builtin_amdgcn_exp2f(sv[kk][e] - m[r]) * inv[r];
; #pragma unroll
;         for (int kk = 0; kk < 2; ++kk) { g1s[kk] += pv[kk][0] + pv[kk][1] + pv[kk][2] + 0.5f * pv[kk][3]; p3s[kk] += 0.5f * pv[kk][3]; }
;       } else {
;         const float mxa = fmaxf(fmaxf(sv[0][0], sv[0][1]), sv[0][2]), mxb = fmaxf(fmaxf(sv[0][3], sv[1][0]), sv[1][1]);
;         float mx = fmaxf(fmaxf(fmaxf(sv[1][2], sv[1][3]), mxa), mxb);
;         if (MODE == 2) mx = selok ? mx : -__builtin_inff();
;         if (__any(mx > m[r] + 8.0f)) {
;           mx = fmaxf(mx, __shfl_xor(mx, 16)); mx = fmaxf(mx, __shfl_xor(mx, 32));
;           const float mn = fmaxf(m[r], mx), al = __builtin_amdgcn_exp2f(m[r] - mn);
;           m[r] = mn; l[r] *= al;
;     ...
;         const float me = (MODE == 2) ? (selok ? m[r] : __builtin_inff()) : m[r];
;         float ps = 0.f;
; #pragma unroll
;         for (int kk = 0; kk < 2; ++kk)
; #pragma unroll
;           for (int e = 0; e < 4; ++e) { pv[kk][e] = __builtin_amdgcn_exp2f(sv[kk][e] - me); ps += pv[kk][e]; }
;         l[r] += ps;
;       }
.LBB0_439:
	v_cndmask_b32_e64 v98, v88, v228, s[36:37]
	v_sub_f32_e32 v85, v87, v98
	v_exp_f32_e32 v85, v85
	v_sub_f32_e32 v86, v86, v98
	v_exp_f32_e32 v86, v86
	v_sub_f32_e32 v83, v83, v98
	v_add_f32_e32 v87, 0, v85
	v_sub_f32_e32 v82, v82, v98
	v_add_f32_e32 v88, v86, v87
	v_exp_f32_e32 v87, v83
	v_sub_f32_e32 v81, v81, v98
	v_exp_f32_e32 v89, v81
	v_sub_f32_e32 v80, v80, v98
	v_add_f32_e32 v83, v87, v88
	v_exp_f32_e32 v88, v82
	v_exp_f32_e32 v96, v80
	v_add_f32_e32 v82, v88, v83
	v_add_f32_e32 v81, v89, v82
	v_add_f32_e32 v80, v96, v81
	v_sub_f32_e32 v81, v97, v98
	v_exp_f32_e32 v97, v81
	v_sub_f32_e32 v81, v84, v98
	v_exp_f32_e32 v84, v81
	v_add_f32_e32 v80, v97, v80
	v_add_f32_e32 v80, v84, v80
	v_add_f32_e32 v190, v190, v80
	s_waitcnt lgkmcnt(3)
	v_fmamk_f32 v81, v76, 0x3e38aa3b, v141
	v_fmamk_f32 v80, v77, 0x3e38aa3b, v140
	s_waitcnt lgkmcnt(2)
	v_fmamk_f32 v78, v78, 0x3e38aa3b, v143
	v_fmamk_f32 v82, v79, 0x3e38aa3b, v142
	s_waitcnt lgkmcnt(1)
	v_fmamk_f32 v77, v72, 0x3e38aa3b, v145
	v_fmamk_f32 v76, v73, 0x3e38aa3b, v144
	s_waitcnt lgkmcnt(0)
	v_fmamk_f32 v73, v74, 0x3e38aa3b, v149
	v_fmamk_f32 v72, v75, 0x3e38aa3b, v148
	v_max3_f32 v74, v81, v80, v78
	v_max3_f32 v75, v82, v77, v76
	v_max_f32_e32 v79, v73, v72
	v_max3_f32 v74, v79, v74, v75
	v_cndmask_b32_e64 v74, v74, v225, s[36:37]
	v_add_f32_e32 v75, 0x41000000, v189
	v_cmp_gt_f32_e32 vcc, v74, v75
	s_cbranch_vccz .LBB0_441
	ds_bpermute_b32 v75, v233, v74
	v_max_f32_e32 v74, v74, v74
	s_waitcnt lgkmcnt(0)
	v_max_f32_e32 v75, v75, v75
	v_max_f32_e32 v74, v74, v75
	ds_bpermute_b32 v75, v234, v74
	s_waitcnt lgkmcnt(0)
	v_max3_f32 v74, v189, v74, v75
	v_sub_f32_e32 v75, v189, v74
	v_exp_f32_e32 v98, v75
	v_mov_b32_e32 v189, v74
	v_mul_f32_e32 v191, v191, v98
	v_pk_mul_f32 v[22:23], v[22:23], v[98:99] op_sel_hi:[1,0]
	v_pk_mul_f32 v[20:21], v[20:21], v[98:99] op_sel_hi:[1,0]
	v_pk_mul_f32 v[30:31], v[30:31], v[98:99] op_sel_hi:[1,0]
	v_pk_mul_f32 v[28:29], v[28:29], v[98:99] op_sel_hi:[1,0]
	v_pk_mul_f32 v[38:39], v[38:39], v[98:99] op_sel_hi:[1,0]
	v_pk_mul_f32 v[36:37], v[36:37], v[98:99] op_sel_hi:[1,0]
	v_pk_mul_f32 v[46:47], v[46:47], v[98:99] op_sel_hi:[1,0]
	v_pk_mul_f32 v[44:45], v[44:45], v[98:99] op_sel_hi:[1,0]
	s_branch .LBB0_442

; template <int MODE>
; __device__ __forceinline__ void nsa_compute(int cur, int buf, int t, int hl, u64 mymask, const bf16x8 (&Qf)[2][2], f32x4 (&O)[4][2], float (&m)[2], float (&l)[2],
;                                             const float (&inv)[2], float* impw, char* lds) {
;     ...
; #pragma unroll
;     for (int ks = 0; ks < 2; ++ks)
; #pragma unroll
;       for (int kk = 0; kk < 2; ++kk) kfr[ks][kk] = *(const bf16x8*)(kt + (32 * s2 + 16 * kk + fr) * 128 + (((ks * 4 + fq) ^ (fr & 7)) << 4));
;     __builtin_amdgcn_s_setprio(1);
; #pragma unroll
;     for (int ks = 0; ks < 2; ++ks)
; #pragma unroll
;       for (int kk = 0; kk < 2; ++kk)
; #pragma unroll
;         for (int r = 0; r < 2; ++r) S[kk][r] = mfma16(kfr[ks][kk], Qf[r][ks], S[kk][r]);
;     __builtin_amdgcn_s_setprio(0);
;     bf16x8 Pf[2];
;     float g1s[2] = {0.f, 0.f}, p3s[2] = {0.f, 0.f};
; #pragma unroll
;     for (int r = 0; r < 2; ++r) {
;       float sv[2][4];
; #pragma unroll
;       for (int kk = 0; kk < 2; ++kk)
; #pragma unroll
;         for (int e = 0; e < 4; ++e) {
;     ...
;         const float me = (MODE == 2) ? (selok ? m[r] : __builtin_inff()) : m[r];
;         float ps = 0.f;
; #pragma unroll
;         for (int kk = 0; kk < 2; ++kk)
; #pragma unroll
;           for (int e = 0; e < 4; ++e) { pv[kk][e] = __builtin_amdgcn_exp2f(sv[kk][e] - me); ps += pv[kk][e]; }
;         l[r] += ps;
;       }
;       if (MODE != 0) {
;         const unsigned w0 = pk2(pv[0][0], pv[0][1]), w1 = pk2(pv[0][2], pv[0][3]), w2 = pk2(pv[1][0], pv[1][1]), w3 = pk2(pv[1][2], pv[1][3]);
;         u32x4 pw; pw.x = w0; pw.y = w1; pw.z = w2; pw.w = w3;
;         Pf[r] = __builtin_bit_cast(bf16x8, pw);
;       }
;     }
;     if (MODE != 0) {
;       bf16x8 vfr[4];
; #pragma unroll
;       for (int df = 0; df < 4; ++df) {
;         const bf16x4 va = *(const bf16x4*)(vt + (df * 16 + fr) * 68 + 32 * s2 + 4 * fq);
;         const bf16x4 vb = *(const bf16x4*)(vt + (df * 16 + fr) * 68 + 32 * s2 + 16 + 4 * fq);
;         bf16x8 vf; vf[0] = va[0]; vf[1] = va[1]; vf[2] = va[2]; vf[3] = va[3]; vf[4] = vb[0]; vf[5] = vb[1]; vf[6] = vb[2]; vf[7] = vb[3];
;         vfr[df] = vf;
;       }
;       __builtin_amdgcn_s_setprio(1);
; #pragma unroll
;       for (int df = 0; df < 4; ++df)
; #pragma unroll
;         for (int r = 0; r < 2; ++r) O[df][r] = mfma16(vfr[df], Pf[r], O[df][r]);
;       __builtin_amdgcn_s_setprio(0);
.LBB0_442:
	v_cndmask_b32_e64 v74, v74, v228, s[36:37]
	v_sub_f32_e32 v75, v81, v74
	v_exp_f32_e32 v75, v75
	v_sub_f32_e32 v80, v80, v74
	v_exp_f32_e32 v80, v80
	v_sub_f32_e32 v78, v78, v74
	v_exp_f32_e32 v78, v78
	v_sub_f32_e32 v81, v82, v74
	v_exp_f32_e32 v81, v81
	v_sub_f32_e32 v77, v77, v74
	v_add_f32_e32 v79, 0, v75
	v_exp_f32_e32 v77, v77
	v_sub_f32_e32 v76, v76, v74
	v_add_f32_e32 v79, v80, v79
	v_exp_f32_e32 v76, v76
	v_sub_f32_e32 v73, v73, v74
	v_add_f32_e32 v79, v78, v79
	v_exp_f32_e32 v73, v73
	v_sub_f32_e32 v72, v72, v74
	v_add_f32_e32 v79, v81, v79
	v_exp_f32_e32 v72, v72
	v_add_f32_e32 v79, v77, v79
	v_add_f32_e32 v79, v76, v79
	v_add_f32_e32 v79, v73, v79
	s_lshl_b32 s17, s74, 9
	v_add_f32_e32 v74, v72, v79
	v_cvt_pk_bf16_f32 v101, v73, v72
	v_mul_u32_u24_e32 v72, 0x44, v94
	s_add_i32 s71, s63, s17
	v_lshlrev_b32_e32 v72, 1, v72
	v_lshlrev_b32_e32 v73, 1, v95
	v_add3_u32 v72, s71, v72, v73
	v_add_u32_e32 v94, 0x4000, v72
	v_cvt_pk_bf16_f32 v87, v87, v88
	v_cvt_pk_bf16_f32 v88, v89, v96
	v_cvt_pk_bf16_f32 v89, v97, v84
	v_cvt_pk_bf16_f32 v99, v78, v81
	v_cvt_pk_bf16_f32 v100, v77, v76
	ds_read2_b64 v[76:79], v94 offset1:4
	v_add_u32_e32 v95, 0x4800, v72
	v_add_u32_e32 v96, 0x5000, v72
	v_add_u32_e32 v97, 0x5800, v72
	ds_read2_b64 v[102:105], v95 offset0:16 offset1:20
	ds_read2_b64 v[106:109], v96 offset0:32 offset1:36
	ds_read2_b64 v[110:113], v97 offset0:48 offset1:52
	v_cvt_pk_bf16_f32 v86, v85, v86
	v_add_f32_e32 v191, v191, v74
	v_cvt_pk_bf16_f32 v98, v75, v80
	s_setprio 1
	s_waitcnt lgkmcnt(3)
	v_mfma_f32_16x16x32_bf16 v[72:75], v[76:79], v[86:89], v[16:19]
	v_mfma_f32_16x16x32_bf16 v[80:83], v[76:79], v[98:101], v[20:23]
	s_waitcnt lgkmcnt(2)
	v_mfma_f32_16x16x32_bf16 v[24:27], v[102:105], v[86:89], v[24:27]
	v_mfma_f32_16x16x32_bf16 v[76:79], v[102:105], v[98:101], v[28:31]
	s_waitcnt lgkmcnt(1)
	v_mfma_f32_16x16x32_bf16 v[20:23], v[106:109], v[86:89], v[32:35]
	v_mfma_f32_16x16x32_bf16 v[32:35], v[106:109], v[98:101], v[36:39]
	s_waitcnt lgkmcnt(0)
	v_mfma_f32_16x16x32_bf16 v[16:19], v[110:113], v[86:89], v[40:43]
	v_mfma_f32_16x16x32_bf16 v[28:31], v[110:113], v[98:101], v[44:47]
	s_setprio 0
	s_nop 0
	v_add_u32_e32 v40, v92, v91
	v_add_u32_e32 v84, v93, v91
	ds_read_b128 v[36:39], v40 offset:4096
	ds_read_b128 v[40:43], v40 offset:6144
	ds_read_b128 v[44:47], v84 offset:4096
	ds_read_b128 v[84:87], v84 offset:6144
	v_add_u32_e32 v251, 0x8400, v90
	v_add_u32_e32 v250, 0xc500, v90
	ds_read2_b32 v[138:139], v251 offset0:31 offset1:32
	ds_read2_b32 v[140:141], v251 offset0:29 offset1:30
	ds_read2_b32 v[142:143], v251 offset0:15 offset1:16
	ds_read2_b32 v[148:149], v251 offset0:13 offset1:14
	ds_read2_b32 v[150:151], v250 offset0:31 offset1:32
	ds_read2_b32 v[152:153], v250 offset0:29 offset1:30
	ds_read2_b32 v[154:155], v250 offset0:15 offset1:16
	ds_read2_b32 v[156:157], v250 offset0:13 offset1:14
	s_setprio 1
	s_waitcnt lgkmcnt(11)
	v_mfma_f32_16x16x32_bf16 v[98:101], v[36:39], v[0:3], 0
	v_mfma_f32_16x16x32_bf16 v[36:39], v[36:39], v[8:11], 0
	s_waitcnt lgkmcnt(10)
	v_mfma_f32_16x16x32_bf16 v[106:109], v[40:43], v[8:11], 0
	v_mfma_f32_16x16x32_bf16 v[102:105], v[40:43], v[0:3], 0
	s_waitcnt lgkmcnt(9)
	v_mfma_f32_16x16x32_bf16 v[40:43], v[44:47], v[12:15], v[36:39]
	s_waitcnt lgkmcnt(8)
	v_mfma_f32_16x16x32_bf16 v[36:39], v[84:87], v[12:15], v[106:109]
	v_mfma_f32_16x16x32_bf16 v[98:101], v[44:47], v[4:7], v[98:101]
	v_mfma_f32_16x16x32_bf16 v[102:105], v[84:87], v[4:7], v[102:105]
	s_setprio 0
	s_waitcnt lgkmcnt(7)
	s_nop 4
	v_fmamk_f32 v91, v98, 0x3e38aa3b, v139
	v_fmamk_f32 v84, v99, 0x3e38aa3b, v138
	s_waitcnt lgkmcnt(6)
	v_fmamk_f32 v85, v100, 0x3e38aa3b, v141
	v_fmamk_f32 v46, v101, 0x3e38aa3b, v140
	s_waitcnt lgkmcnt(5)
	v_fmamk_f32 v45, v102, 0x3e38aa3b, v143
	v_fmamk_f32 v44, v103, 0x3e38aa3b, v142
	v_max3_f32 v47, v91, v84, v85
	s_waitcnt lgkmcnt(4)
	v_fmamk_f32 v92, v104, 0x3e38aa3b, v149
	v_fmamk_f32 v86, v105, 0x3e38aa3b, v148
	v_max3_f32 v87, v46, v45, v44
	v_max_f32_e32 v88, v92, v86
	v_max3_f32 v47, v88, v47, v87
	v_cndmask_b32_e64 v47, v47, v225, s[36:37]
	v_add_f32_e32 v87, 0x41000000, v188
	v_cmp_gt_f32_e32 vcc, v47, v87
	s_cbranch_vccz .LBB0_444
	ds_bpermute_b32 v87, v233, v47
	v_max_f32_e32 v47, v47, v47
	v_mov_b32_e32 v89, v189
	s_waitcnt lgkmcnt(0)
	v_max_f32_e32 v87, v87, v87
	v_max_f32_e32 v47, v47, v87
	ds_bpermute_b32 v87, v234, v47
	s_waitcnt lgkmcnt(0)
	v_max3_f32 v88, v188, v47, v87
	v_sub_f32_e32 v47, v188, v88
	v_exp_f32_e32 v98, v47
	v_mov_b64_e32 v[188:189], v[88:89]
	v_mul_f32_e32 v190, v190, v98
	v_pk_mul_f32 v[74:75], v[74:75], v[98:99] op_sel_hi:[1,0]
	v_pk_mul_f32 v[72:73], v[72:73], v[98:99] op_sel_hi:[1,0]
	v_pk_mul_f32 v[26:27], v[26:27], v[98:99] op_sel_hi:[1,0]
	v_pk_mul_f32 v[24:25], v[24:25], v[98:99] op_sel_hi:[1,0]
	v_pk_mul_f32 v[22:23], v[22:23], v[98:99] op_sel_hi:[1,0]
	v_pk_mul_f32 v[20:21], v[20:21], v[98:99] op_sel_hi:[1,0]
	v_pk_mul_f32 v[18:19], v[18:19], v[98:99] op_sel_hi:[1,0]
	v_pk_mul_f32 v[16:17], v[16:17], v[98:99] op_sel_hi:[1,0]
	s_branch .LBB0_445

; template <int MODE>
; __device__ __forceinline__ void nsa_compute(int cur, int buf, int t, int hl, u64 mymask, const bf16x8 (&Qf)[2][2], f32x4 (&O)[4][2], float (&m)[2], float (&l)[2],
;                                             const float (&inv)[2], float* impw, char* lds) {
;     ...
;       for (int kk = 0; kk < 2; ++kk)
; #pragma unroll
;         for (int e = 0; e < 4; ++e) {
;           const int off = 32 * s2 + 16 * kk + e;
;           int idx;
;           if (MODE <= 1) { idx = base - 16 * off; idx = idx > 0 ? idx : 0; } else idx = base - off;
;           sv[kk][e] = S[kk][r][e] * (0.125f * LOG2E) + tb[r * TS + idx];
;         }
;       float pv[2][4];
;       if (MODE == 1) {
; #pragma unroll
;         for (int kk = 0; kk < 2; ++kk)
; #pragma unroll
;           for (int e = 0; e < 4; ++e) pv[kk][e] = __builtin_amdgcn_exp2f(sv[kk][e] - m[r]) * inv[r];
; #pragma unroll
;         for (int kk = 0; kk < 2; ++kk) { g1s[kk] += pv[kk][0] + pv[kk][1] + pv[kk][2] + 0.5f * pv[kk][3]; p3s[kk] += 0.5f * pv[kk][3]; }
;       } else {
;         const float mxa = fmaxf(fmaxf(sv[0][0], sv[0][1]), sv[0][2]), mxb = fmaxf(fmaxf(sv[0][3], sv[1][0]), sv[1][1]);
;         float mx = fmaxf(fmaxf(fmaxf(sv[1][2], sv[1][3]), mxa), mxb);
;         if (MODE == 2) mx = selok ? mx : -__builtin_inff();
;         if (__any(mx > m[r] + 8.0f)) {
;           mx = fmaxf(mx, __shfl_xor(mx, 16)); mx = fmaxf(mx, __shfl_xor(mx, 32));
;           const float mn = fmaxf(m[r], mx), al = __builtin_amdgcn_exp2f(m[r] - mn);
;           m[r] = mn; l[r] *= al;
;           if (MODE != 0) {
; #pragma unroll
;             for (int df = 0; df < 4; ++df) O[df][r] *= al;
;           }
;         }
;         const float me = (MODE == 2) ? (selok ? m[r] : __builtin_inff()) : m[r];
;         float ps = 0.f;
; #pragma unroll
;         for (int kk = 0; kk < 2; ++kk)
; #pragma unroll
;           for (int e = 0; e < 4; ++e) { pv[kk][e] = __builtin_amdgcn_exp2f(sv[kk][e] - me); ps += pv[kk][e]; }
;         l[r] += ps;
.LBB0_445:
	v_cndmask_b32_e64 v93, v88, v228, s[36:37]
	v_sub_f32_e32 v47, v91, v93
	v_exp_f32_e32 v47, v47
	v_sub_f32_e32 v84, v84, v93
	v_exp_f32_e32 v84, v84
	v_sub_f32_e32 v85, v85, v93
	v_exp_f32_e32 v85, v85
	v_sub_f32_e32 v46, v46, v93
	v_exp_f32_e32 v46, v46
	v_add_f32_e32 v87, 0, v47
	v_add_f32_e32 v87, v84, v87
	v_add_f32_e32 v87, v85, v87
	v_sub_f32_e32 v45, v45, v93
	v_add_f32_e32 v88, v46, v87
	v_exp_f32_e32 v87, v45
	v_sub_f32_e32 v44, v44, v93
	v_add_f32_e32 v45, v87, v88
	v_exp_f32_e32 v88, v44
	s_nop 0
	v_add_f32_e32 v44, v88, v45
	v_sub_f32_e32 v45, v92, v93
	v_exp_f32_e32 v89, v45
	v_sub_f32_e32 v45, v86, v93
	v_exp_f32_e32 v86, v45
	v_add_f32_e32 v44, v89, v44
	v_add_f32_e32 v44, v86, v44
	v_add_f32_e32 v190, v190, v44
	s_waitcnt lgkmcnt(3)
	v_fmamk_f32 v45, v40, 0x3e38aa3b, v151
	v_fmamk_f32 v44, v41, 0x3e38aa3b, v150
	s_waitcnt lgkmcnt(2)
	v_fmamk_f32 v41, v42, 0x3e38aa3b, v153
	v_fmamk_f32 v40, v43, 0x3e38aa3b, v152
	s_waitcnt lgkmcnt(1)
	v_fmamk_f32 v43, v36, 0x3e38aa3b, v155
	v_fmamk_f32 v42, v37, 0x3e38aa3b, v154
	s_waitcnt lgkmcnt(0)
	v_fmamk_f32 v90, v38, 0x3e38aa3b, v157
	v_fmamk_f32 v36, v39, 0x3e38aa3b, v156
	v_max3_f32 v37, v45, v44, v41
	v_max3_f32 v38, v40, v43, v42
	v_max_f32_e32 v39, v90, v36
	v_max3_f32 v37, v39, v37, v38
	v_cndmask_b32_e64 v37, v37, v225, s[36:37]
	v_add_f32_e32 v38, 0x41000000, v189
	v_cmp_gt_f32_e32 vcc, v37, v38
	s_cbranch_vccz .LBB0_447
	ds_bpermute_b32 v38, v233, v37
	v_max_f32_e32 v37, v37, v37
	s_waitcnt lgkmcnt(0)
	v_max_f32_e32 v38, v38, v38
	v_max_f32_e32 v37, v37, v38
	ds_bpermute_b32 v38, v234, v37
	s_waitcnt lgkmcnt(0)
	v_max3_f32 v37, v189, v37, v38
	v_sub_f32_e32 v38, v189, v37
	v_exp_f32_e32 v38, v38
	v_mov_b32_e32 v189, v37
	v_mul_f32_e32 v191, v191, v38
	v_pk_mul_f32 v[82:83], v[82:83], v[38:39] op_sel_hi:[1,0]
	v_pk_mul_f32 v[80:81], v[80:81], v[38:39] op_sel_hi:[1,0]
	v_pk_mul_f32 v[78:79], v[78:79], v[38:39] op_sel_hi:[1,0]
	v_pk_mul_f32 v[76:77], v[76:77], v[38:39] op_sel_hi:[1,0]
	v_pk_mul_f32 v[34:35], v[34:35], v[38:39] op_sel_hi:[1,0]
	v_pk_mul_f32 v[32:33], v[32:33], v[38:39] op_sel_hi:[1,0]
	v_pk_mul_f32 v[30:31], v[30:31], v[38:39] op_sel_hi:[1,0]
	v_pk_mul_f32 v[28:29], v[28:29], v[38:39] op_sel_hi:[1,0]
	v_mov_b64_e32 v[144:145], v[190:191]
	s_branch .LBB0_448

; template <int MODE>
; __device__ __forceinline__ void nsa_compute(int cur, int buf, int t, int hl, u64 mymask, const bf16x8 (&Qf)[2][2], f32x4 (&O)[4][2], float (&m)[2], float (&l)[2],
;                                             const float (&inv)[2], float* impw, char* lds) {
;     ...
;   const bool selok = (MODE == 2) ? (((mymask >> cur) & 1ull) != 0ull) : true;
;   const float* tb = (MODE == 3) ? (const float*)(lds + NSA_TW) + hl * 640 : (const float*)(lds + NSA_T) + hl * 4160;
;   constexpr int TS = (MODE == 3) ? 640 : 4160;
;   const int base = (MODE <= 1) ? (t - 31 - 16 * (cur * 64 + 4 * fq) + 64) : (t - cur * 64 - 4 * fq + 64);
; #pragma unroll
;   for (int s2 = 0; s2 < 2; ++s2) {
;     f32x4 S[2][2] = {};
;     bf16x8 kfr[2][2];
; #pragma unroll
;     for (int ks = 0; ks < 2; ++ks)
; #pragma unroll
;       for (int kk = 0; kk < 2; ++kk) kfr[ks][kk] = *(const bf16x8*)(kt + (32 * s2 + 16 * kk + fr) * 128 + (((ks * 4 + fq) ^ (fr & 7)) << 4));
;     __builtin_amdgcn_s_setprio(1);
; #pragma unroll
;     for (int ks = 0; ks < 2; ++ks)
; #pragma unroll
;       for (int kk = 0; kk < 2; ++kk)
; #pragma unroll
;         for (int r = 0; r < 2; ++r) S[kk][r] = mfma16(kfr[ks][kk], Qf[r][ks], S[kk][r]);
;     __builtin_amdgcn_s_setprio(0);
;     bf16x8 Pf[2];
;     float g1s[2] = {0.f, 0.f}, p3s[2] = {0.f, 0.f};
; #pragma unroll
;     for (int r = 0; r < 2; ++r) {
;       float sv[2][4];
; #pragma unroll
;       for (int kk = 0; kk < 2; ++kk)
; #pragma unroll
;         for (int e = 0; e < 4; ++e) {
;           const int off = 32 * s2 + 16 * kk + e;
;           int idx;
;           if (MODE <= 1) { idx = base - 16 * off; idx = idx > 0 ? idx : 0; } else idx = base - off;
;           sv[kk][e] = S[kk][r][e] * (0.125f * LOG2E) + tb[r * TS + idx];
;         }
;       float pv[2][4];
;       if (MODE == 1) {
; #pragma unroll
;         for (int kk = 0; kk < 2; ++kk)
; #pragma unroll
;           for (int e = 0; e < 4; ++e) pv[kk][e] = __builtin_amdgcn_exp2f(sv[kk][e] - m[r]) * inv[r];
; #pragma unroll
;         for (int kk = 0; kk < 2; ++kk) { g1s[kk] += pv[kk][0] + pv[kk][1] + pv[kk][2] + 0.5f * pv[kk][3]; p3s[kk] += 0.5f * pv[kk][3]; }
;       } else {
;         const float mxa = fmaxf(fmaxf(sv[0][0], sv[0][1]), sv[0][2]), mxb = fmaxf(fmaxf(sv[0][3], sv[1][0]), sv[1][1]);
;         float mx = fmaxf(fmaxf(fmaxf(sv[1][2], sv[1][3]), mxa), mxb);
.LBB0_452:
	v_add_f32_e32 v16, 0, v37
	v_add_f32_e32 v16, v38, v16
	v_add_f32_e32 v16, v39, v16
	v_add_f32_e32 v16, v40, v16
	v_add_f32_e32 v16, v41, v16
	v_add_f32_e32 v16, v42, v16
	v_add_f32_e32 v16, v43, v16
	v_add_f32_e32 v16, v36, v16
	s_cmp_lt_i32 s16, 0
	v_add_f32_e32 v145, v145, v16
	s_cbranch_scc1 .LBB0_435
	s_lshl_b64 s[30:31], 1, s16
	v_mov_b32 v18, v179
	v_and_b32_e32 v17, s31, v187
	v_lshrrev_b32_e32 v19, 4, v18
	v_bfe_u32 v24, v18, 4, 2
	v_and_b32_e32 v16, s30, v186
	v_and_b32_e32 v25, 7, v18
	v_and_b32_e32 v117, 15, v18
	s_lshl_b32 s72, s74, 13
	v_cmp_eq_u64_e64 s[36:37], 0, v[16:17]
	v_lshlrev_b32_e32 v118, 2, v24
	v_bitop3_b32 v16, v19, v25, 3 bitop3:0x6c
	v_bitop3_b32 v24, v24, v25, 4 bitop3:0x36
	v_lshlrev_b32_e32 v114, 7, v117
	v_lshl_or_b32 v115, v16, 4, s72
	v_lshl_or_b32 v116, v24, 4, s72
	v_or_b32_e32 v20, v115, v114
	v_or_b32_e32 v28, v116, v114
	ds_read_b128 v[16:19], v20
	ds_read_b128 v[20:23], v20 offset:2048
	ds_read_b128 v[24:27], v28
	ds_read_b128 v[28:31], v28 offset:2048
	v_sub_u32_e32 v251, v180, v118
	v_lshl_add_u32 v251, v251, 2, v181
	s_lshl_b32 s16, s16, 8
	v_subrev_u32_e32 v250, s16, v251
	v_add_u32_e32 v249, 0x8400, v250
	v_add_u32_e32 v248, 0xc500, v250
	ds_read2_b32 v[148:149], v249 offset0:63 offset1:64
	ds_read2_b32 v[150:151], v249 offset0:61 offset1:62
	ds_read2_b32 v[152:153], v249 offset0:47 offset1:48
	ds_read2_b32 v[154:155], v249 offset0:45 offset1:46
	ds_read2_b32 v[156:157], v248 offset0:63 offset1:64
	ds_read2_b32 v[168:169], v248 offset0:61 offset1:62
	ds_read2_b32 v[170:171], v248 offset0:47 offset1:48
	ds_read2_b32 v[172:173], v248 offset0:45 offset1:46
	s_setprio 1
	s_waitcnt lgkmcnt(11)
	v_mfma_f32_16x16x32_bf16 v[32:35], v[16:19], v[0:3], 0
	v_mfma_f32_16x16x32_bf16 v[16:19], v[16:19], v[8:11], 0
	s_waitcnt lgkmcnt(10)
	v_mfma_f32_16x16x32_bf16 v[40:43], v[20:23], v[0:3], 0
	v_mfma_f32_16x16x32_bf16 v[20:23], v[20:23], v[8:11], 0
	s_waitcnt lgkmcnt(9)
	v_mfma_f32_16x16x32_bf16 v[36:39], v[24:27], v[12:15], v[16:19]
	s_waitcnt lgkmcnt(8)
	v_mfma_f32_16x16x32_bf16 v[16:19], v[28:31], v[4:7], v[40:43]
	v_mfma_f32_16x16x32_bf16 v[28:31], v[28:31], v[12:15], v[20:23]
	v_mfma_f32_16x16x32_bf16 v[32:35], v[24:27], v[4:7], v[32:35]
	s_setprio 0
	s_nop 0
	v_sub_u32_e32 v20, v180, v118
	v_lshl_add_u32 v20, v20, 2, v181
	v_subrev_u32_e32 v122, s16, v20
	s_waitcnt lgkmcnt(7)
	s_nop 1
	v_fmamk_f32 v47, v32, 0x3e38aa3b, v149
	v_fmamk_f32 v46, v33, 0x3e38aa3b, v148
	s_waitcnt lgkmcnt(6)
	v_fmamk_f32 v43, v34, 0x3e38aa3b, v151
	v_fmamk_f32 v42, v35, 0x3e38aa3b, v150
	s_waitcnt lgkmcnt(5)
	v_fmamk_f32 v41, v16, 0x3e38aa3b, v153
	v_fmamk_f32 v40, v17, 0x3e38aa3b, v152
	v_max3_f32 v16, v47, v46, v43
	v_max3_f32 v17, v42, v41, v40
	s_waitcnt lgkmcnt(4)
	v_fmamk_f32 v45, v18, 0x3e38aa3b, v155
	v_fmamk_f32 v44, v19, 0x3e38aa3b, v154
	v_max_f32_e32 v18, v45, v44
	v_max3_f32 v16, v18, v16, v17
	v_cndmask_b32_e64 v16, v16, v225, s[36:37]
	v_add_f32_e32 v17, 0x41000000, v188
	v_cmp_gt_f32_e32 vcc, v16, v17
	s_cbranch_vccz .LBB0_455
	ds_bpermute_b32 v17, v233, v16
	v_max_f32_e32 v16, v16, v16
	v_mov_b32_e32 v105, v189
	v_mov_b32_e32 v147, v145
	s_waitcnt lgkmcnt(0)
	v_max_f32_e32 v17, v17, v17
	v_max_f32_e32 v16, v16, v17
	ds_bpermute_b32 v17, v234, v16
	s_waitcnt lgkmcnt(0)
	v_max3_f32 v104, v188, v16, v17
	v_sub_f32_e32 v16, v188, v104
	v_exp_f32_e32 v32, v16
	v_mov_b64_e32 v[188:189], v[104:105]
	v_mul_f32_e32 v146, v144, v32
	v_pk_mul_f32 v[26:27], v[90:91], v[32:33] op_sel_hi:[1,0]
	v_pk_mul_f32 v[24:25], v[88:89], v[32:33] op_sel_hi:[1,0]
	v_pk_mul_f32 v[18:19], v[102:103], v[32:33] op_sel_hi:[1,0]
	v_pk_mul_f32 v[16:17], v[100:101], v[32:33] op_sel_hi:[1,0]
	v_pk_mul_f32 v[22:23], v[94:95], v[32:33] op_sel_hi:[1,0]
	v_pk_mul_f32 v[20:21], v[92:93], v[32:33] op_sel_hi:[1,0]
	v_pk_mul_f32 v[34:35], v[82:83], v[32:33] op_sel_hi:[1,0]
	v_pk_mul_f32 v[32:33], v[80:81], v[32:33] op_sel_hi:[1,0]
	s_branch .LBB0_456

; template <int MODE>
; __device__ __forceinline__ void nsa_compute(int cur, int buf, int t, int hl, u64 mymask, const bf16x8 (&Qf)[2][2], f32x4 (&O)[4][2], float (&m)[2], float (&l)[2],
;                                             const float (&inv)[2], float* impw, char* lds) {
;     ...
;       for (int kk = 0; kk < 2; ++kk)
; #pragma unroll
;         for (int e = 0; e < 4; ++e) {
;           const int off = 32 * s2 + 16 * kk + e;
;           int idx;
;           if (MODE <= 1) { idx = base - 16 * off; idx = idx > 0 ? idx : 0; } else idx = base - off;
;           sv[kk][e] = S[kk][r][e] * (0.125f * LOG2E) + tb[r * TS + idx];
;         }
;       float pv[2][4];
;       if (MODE == 1) {
; #pragma unroll
;         for (int kk = 0; kk < 2; ++kk)
; #pragma unroll
;           for (int e = 0; e < 4; ++e) pv[kk][e] = __builtin_amdgcn_exp2f(sv[kk][e] - m[r]) * inv[r];
; #pragma unroll
;         for (int kk = 0; kk < 2; ++kk) { g1s[kk] += pv[kk][0] + pv[kk][1] + pv[kk][2] + 0.5f * pv[kk][3]; p3s[kk] += 0.5f * pv[kk][3]; }
;       } else {
;         const float mxa = fmaxf(fmaxf(sv[0][0], sv[0][1]), sv[0][2]), mxb = fmaxf(fmaxf(sv[0][3], sv[1][0]), sv[1][1]);
;         float mx = fmaxf(fmaxf(fmaxf(sv[1][2], sv[1][3]), mxa), mxb);
;         if (MODE == 2) mx = selok ? mx : -__builtin_inff();
;         if (__any(mx > m[r] + 8.0f)) {
;           mx = fmaxf(mx, __shfl_xor(mx, 16)); mx = fmaxf(mx, __shfl_xor(mx, 32));
;           const float mn = fmaxf(m[r], mx), al = __builtin_amdgcn_exp2f(m[r] - mn);
;           m[r] = mn; l[r] *= al;
;           if (MODE != 0) {
; #pragma unroll
;             for (int df = 0; df < 4; ++df) O[df][r] *= al;
;           }
;         }
;         const float me = (MODE == 2) ? (selok ? m[r] : __builtin_inff()) : m[r];
;         float ps = 0.f;
; #pragma unroll
;         for (int kk = 0; kk < 2; ++kk)
; #pragma unroll
;           for (int e = 0; e < 4; ++e) { pv[kk][e] = __builtin_amdgcn_exp2f(sv[kk][e] - me); ps += pv[kk][e]; }
;         l[r] += ps;
.LBB0_456:
	v_cndmask_b32_e64 v104, v104, v228, s[36:37]
	v_sub_f32_e32 v47, v47, v104
	v_exp_f32_e32 v119, v47
	v_sub_f32_e32 v46, v46, v104
	v_exp_f32_e32 v120, v46
	v_sub_f32_e32 v43, v43, v104
	v_exp_f32_e32 v121, v43
	v_sub_f32_e32 v42, v42, v104
	v_exp_f32_e32 v123, v42
	v_sub_f32_e32 v41, v41, v104
	v_add_f32_e32 v47, 0, v119
	v_exp_f32_e32 v124, v41
	v_sub_f32_e32 v40, v40, v104
	v_add_f32_e32 v46, v120, v47
	v_exp_f32_e32 v125, v40
	v_add_f32_e32 v43, v121, v46
	v_add_f32_e32 v42, v123, v43
	v_add_f32_e32 v41, v124, v42
	v_add_f32_e32 v40, v125, v41
	v_sub_f32_e32 v41, v45, v104
	v_exp_f32_e32 v126, v41
	v_sub_f32_e32 v41, v44, v104
	v_exp_f32_e32 v127, v41
	v_add_f32_e32 v40, v126, v40
	v_add_f32_e32 v40, v127, v40
	v_add_f32_e32 v146, v146, v40
	s_waitcnt lgkmcnt(3)
	v_fmamk_f32 v47, v36, 0x3e38aa3b, v157
	v_fmamk_f32 v46, v37, 0x3e38aa3b, v156
	s_waitcnt lgkmcnt(2)
	v_fmamk_f32 v113, v38, 0x3e38aa3b, v169
	v_fmamk_f32 v112, v39, 0x3e38aa3b, v168
	s_waitcnt lgkmcnt(1)
	v_fmamk_f32 v45, v28, 0x3e38aa3b, v171
	v_fmamk_f32 v44, v29, 0x3e38aa3b, v170
	s_waitcnt lgkmcnt(0)
	v_fmamk_f32 v29, v30, 0x3e38aa3b, v173
	v_fmamk_f32 v28, v31, 0x3e38aa3b, v172
	v_max3_f32 v30, v47, v46, v113
	v_max3_f32 v31, v112, v45, v44
	v_max_f32_e32 v36, v29, v28
	v_max3_f32 v30, v36, v30, v31
	v_cndmask_b32_e64 v30, v30, v225, s[36:37]
	v_add_f32_e32 v31, 0x41000000, v189
	v_cmp_gt_f32_e32 vcc, v30, v31
	s_cbranch_vccz .LBB0_458
	ds_bpermute_b32 v31, v233, v30
	v_max_f32_e32 v30, v30, v30
	s_waitcnt lgkmcnt(0)
	v_max_f32_e32 v31, v31, v31
	v_max_f32_e32 v30, v30, v31
	ds_bpermute_b32 v31, v234, v30
	s_waitcnt lgkmcnt(0)
	v_max3_f32 v30, v189, v30, v31
	v_sub_f32_e32 v31, v189, v30
	v_exp_f32_e32 v108, v31
	v_mov_b32_e32 v189, v30
	v_mul_f32_e32 v147, v147, v108
	v_pk_mul_f32 v[38:39], v[98:99], v[108:109] op_sel_hi:[1,0]
	v_pk_mul_f32 v[36:37], v[96:97], v[108:109] op_sel_hi:[1,0]
	v_pk_mul_f32 v[42:43], v[86:87], v[108:109] op_sel_hi:[1,0]
	v_pk_mul_f32 v[40:41], v[84:85], v[108:109] op_sel_hi:[1,0]
	v_pk_mul_f32 v[106:107], v[78:79], v[108:109] op_sel_hi:[1,0]
	v_pk_mul_f32 v[104:105], v[76:77], v[108:109] op_sel_hi:[1,0]
	v_pk_mul_f32 v[110:111], v[74:75], v[108:109] op_sel_hi:[1,0]
	v_pk_mul_f32 v[108:109], v[72:73], v[108:109] op_sel_hi:[1,0]
	s_branch .LBB0_459

; template <int MODE>
; __device__ __forceinline__ void nsa_compute(int cur, int buf, int t, int hl, u64 mymask, const bf16x8 (&Qf)[2][2], f32x4 (&O)[4][2], float (&m)[2], float (&l)[2],
;                                             const float (&inv)[2], float* impw, char* lds) {
;     ...
; #pragma unroll
;     for (int ks = 0; ks < 2; ++ks)
; #pragma unroll
;       for (int kk = 0; kk < 2; ++kk) kfr[ks][kk] = *(const bf16x8*)(kt + (32 * s2 + 16 * kk + fr) * 128 + (((ks * 4 + fq) ^ (fr & 7)) << 4));
;     __builtin_amdgcn_s_setprio(1);
; #pragma unroll
;     for (int ks = 0; ks < 2; ++ks)
; #pragma unroll
;       for (int kk = 0; kk < 2; ++kk)
; #pragma unroll
;         for (int r = 0; r < 2; ++r) S[kk][r] = mfma16(kfr[ks][kk], Qf[r][ks], S[kk][r]);
;     __builtin_amdgcn_s_setprio(0);
;     bf16x8 Pf[2];
;     float g1s[2] = {0.f, 0.f}, p3s[2] = {0.f, 0.f};
; #pragma unroll
;     for (int r = 0; r < 2; ++r) {
;       float sv[2][4];
; #pragma unroll
;       for (int kk = 0; kk < 2; ++kk)
; #pragma unroll
;         for (int e = 0; e < 4; ++e) {
;     ...
;         const float me = (MODE == 2) ? (selok ? m[r] : __builtin_inff()) : m[r];
;         float ps = 0.f;
; #pragma unroll
;         for (int kk = 0; kk < 2; ++kk)
; #pragma unroll
;           for (int e = 0; e < 4; ++e) { pv[kk][e] = __builtin_amdgcn_exp2f(sv[kk][e] - me); ps += pv[kk][e]; }
;         l[r] += ps;
;       }
;       if (MODE != 0) {
;         const unsigned w0 = pk2(pv[0][0], pv[0][1]), w1 = pk2(pv[0][2], pv[0][3]), w2 = pk2(pv[1][0], pv[1][1]), w3 = pk2(pv[1][2], pv[1][3]);
;         u32x4 pw; pw.x = w0; pw.y = w1; pw.z = w2; pw.w = w3;
;         Pf[r] = __builtin_bit_cast(bf16x8, pw);
;       }
;     }
;     if (MODE != 0) {
;       bf16x8 vfr[4];
; #pragma unroll
;       for (int df = 0; df < 4; ++df) {
;         const bf16x4 va = *(const bf16x4*)(vt + (df * 16 + fr) * 68 + 32 * s2 + 4 * fq);
;         const bf16x4 vb = *(const bf16x4*)(vt + (df * 16 + fr) * 68 + 32 * s2 + 16 + 4 * fq);
;         bf16x8 vf; vf[0] = va[0]; vf[1] = va[1]; vf[2] = va[2]; vf[3] = va[3]; vf[4] = vb[0]; vf[5] = vb[1]; vf[6] = vb[2]; vf[7] = vb[3];
;         vfr[df] = vf;
;       }
;       __builtin_amdgcn_s_setprio(1);
; #pragma unroll
;       for (int df = 0; df < 4; ++df)
; #pragma unroll
;         for (int r = 0; r < 2; ++r) O[df][r] = mfma16(vfr[df], Pf[r], O[df][r]);
;       __builtin_amdgcn_s_setprio(0);
.LBB0_459:
	v_cndmask_b32_e64 v30, v30, v228, s[36:37]
	v_sub_f32_e32 v31, v47, v30
	v_exp_f32_e32 v31, v31
	v_sub_f32_e32 v46, v46, v30
	v_exp_f32_e32 v46, v46
	v_sub_f32_e32 v113, v113, v30
	v_exp_f32_e32 v113, v113
	v_sub_f32_e32 v112, v112, v30
	v_exp_f32_e32 v112, v112
	v_sub_f32_e32 v45, v45, v30
	v_add_f32_e32 v47, 0, v31
	v_exp_f32_e32 v45, v45
	v_sub_f32_e32 v44, v44, v30
	v_add_f32_e32 v47, v46, v47
	v_exp_f32_e32 v44, v44
	v_sub_f32_e32 v29, v29, v30
	v_add_f32_e32 v47, v113, v47
	v_exp_f32_e32 v29, v29
	v_sub_f32_e32 v28, v28, v30
	v_add_f32_e32 v47, v112, v47
	v_exp_f32_e32 v28, v28
	v_add_f32_e32 v47, v45, v47
	v_add_f32_e32 v47, v44, v47
	v_add_f32_e32 v47, v29, v47
	s_lshl_b32 s16, s74, 9
	v_add_f32_e32 v30, v28, v47
	v_cvt_pk_bf16_f32 v135, v29, v28
	v_mul_u32_u24_e32 v28, 0x44, v117
	s_add_i32 s73, s72, s16
	v_lshlrev_b32_e32 v28, 1, v28
	v_lshlrev_b32_e32 v29, 1, v118
	v_add3_u32 v28, s73, v28, v29
	v_cvt_pk_bf16_f32 v129, v121, v123
	v_cvt_pk_bf16_f32 v130, v124, v125
	v_add_u32_e32 v123, 0x4000, v28
	v_add_u32_e32 v124, 0x4800, v28
	v_cvt_pk_bf16_f32 v128, v119, v120
	v_cvt_pk_bf16_f32 v131, v126, v127
	v_cvt_pk_bf16_f32 v132, v31, v46
	v_cvt_pk_bf16_f32 v134, v45, v44
	ds_read2_b64 v[44:47], v123 offset1:4
	ds_read2_b64 v[118:121], v124 offset0:16 offset1:20
	v_add_u32_e32 v125, 0x5000, v28
	v_add_u32_e32 v126, 0x5800, v28
	ds_read2_b64 v[136:139], v125 offset0:32 offset1:36
	ds_read2_b64 v[140:143], v126 offset0:48 offset1:52
	v_add_f32_e32 v147, v147, v30
	v_cvt_pk_bf16_f32 v133, v113, v112
	s_setprio 1
	s_waitcnt lgkmcnt(3)
	v_mfma_f32_16x16x32_bf16 v[28:31], v[44:47], v[128:131], v[24:27]
	v_mfma_f32_16x16x32_bf16 v[44:47], v[44:47], v[132:135], v[36:39]
	s_waitcnt lgkmcnt(2)
	v_mfma_f32_16x16x32_bf16 v[24:27], v[118:121], v[128:131], v[16:19]
	v_mfma_f32_16x16x32_bf16 v[40:43], v[118:121], v[132:135], v[40:43]
	s_waitcnt lgkmcnt(1)
	v_mfma_f32_16x16x32_bf16 v[20:23], v[136:139], v[128:131], v[20:23]
	v_mfma_f32_16x16x32_bf16 v[36:39], v[136:139], v[132:135], v[104:107]
	s_waitcnt lgkmcnt(0)
	v_mfma_f32_16x16x32_bf16 v[16:19], v[140:143], v[128:131], v[32:35]
	v_mfma_f32_16x16x32_bf16 v[32:35], v[140:143], v[132:135], v[108:111]
	s_setprio 0
	s_nop 1
	v_add_u32_e32 v108, v115, v114
	v_add_u32_e32 v116, v116, v114
	ds_read_b128 v[104:107], v108 offset:4096
	ds_read_b128 v[108:111], v108 offset:6144
	ds_read_b128 v[112:115], v116 offset:4096
	ds_read_b128 v[116:119], v116 offset:6144
	v_add_u32_e32 v251, 0x8400, v122
	v_add_u32_e32 v250, 0xc500, v122
	ds_read2_b32 v[152:153], v251 offset0:31 offset1:32
	ds_read2_b32 v[154:155], v251 offset0:29 offset1:30
	ds_read2_b32 v[156:157], v251 offset0:15 offset1:16
	ds_read2_b32 v[168:169], v251 offset0:13 offset1:14
	ds_read2_b32 v[170:171], v250 offset0:31 offset1:32
	ds_read2_b32 v[172:173], v250 offset0:29 offset1:30
	ds_read2_b32 v[174:175], v250 offset0:15 offset1:16
	ds_read2_b32 v[192:193], v250 offset0:13 offset1:14
	s_setprio 1
	s_waitcnt lgkmcnt(11)
	v_mfma_f32_16x16x32_bf16 v[128:131], v[104:107], v[0:3], 0
	v_mfma_f32_16x16x32_bf16 v[104:107], v[104:107], v[8:11], 0
	s_waitcnt lgkmcnt(10)
	v_mfma_f32_16x16x32_bf16 v[136:139], v[108:111], v[8:11], 0
	v_mfma_f32_16x16x32_bf16 v[132:135], v[108:111], v[0:3], 0
	s_waitcnt lgkmcnt(9)
	v_mfma_f32_16x16x32_bf16 v[128:131], v[112:115], v[4:7], v[128:131]
	v_mfma_f32_16x16x32_bf16 v[108:111], v[112:115], v[12:15], v[104:107]
	s_waitcnt lgkmcnt(8)
	v_mfma_f32_16x16x32_bf16 v[104:107], v[116:119], v[12:15], v[136:139]
	v_mfma_f32_16x16x32_bf16 v[132:135], v[116:119], v[4:7], v[132:135]
	s_setprio 0
	s_waitcnt lgkmcnt(7)
	s_nop 1
	v_fmamk_f32 v127, v128, 0x3e38aa3b, v153
	v_fmamk_f32 v116, v129, 0x3e38aa3b, v152
	s_waitcnt lgkmcnt(6)
	v_fmamk_f32 v117, v130, 0x3e38aa3b, v155
	v_fmamk_f32 v114, v131, 0x3e38aa3b, v154
	s_waitcnt lgkmcnt(5)
	v_fmamk_f32 v113, v132, 0x3e38aa3b, v157
	v_fmamk_f32 v112, v133, 0x3e38aa3b, v156
	v_max3_f32 v115, v127, v116, v117
	s_waitcnt lgkmcnt(4)
	v_fmamk_f32 v128, v134, 0x3e38aa3b, v169
	v_fmamk_f32 v118, v135, 0x3e38aa3b, v168
	v_max3_f32 v119, v114, v113, v112
	v_max_f32_e32 v120, v128, v118
	v_max3_f32 v115, v120, v115, v119
	v_cndmask_b32_e64 v115, v115, v225, s[36:37]
	v_add_f32_e32 v119, 0x41000000, v188
	v_cmp_gt_f32_e32 vcc, v115, v119
	s_cbranch_vccz .LBB0_461
	ds_bpermute_b32 v119, v233, v115
	v_max_f32_e32 v115, v115, v115
	v_mov_b32_e32 v121, v189
	s_waitcnt lgkmcnt(0)
	v_max_f32_e32 v119, v119, v119
	v_max_f32_e32 v115, v115, v119
	ds_bpermute_b32 v119, v234, v115
	s_waitcnt lgkmcnt(0)
	v_max3_f32 v120, v188, v115, v119
	v_sub_f32_e32 v115, v188, v120
	v_exp_f32_e32 v130, v115
	v_mov_b64_e32 v[188:189], v[120:121]
	v_mul_f32_e32 v146, v146, v130
	v_pk_mul_f32 v[30:31], v[30:31], v[130:131] op_sel_hi:[1,0]
	v_pk_mul_f32 v[28:29], v[28:29], v[130:131] op_sel_hi:[1,0]
	v_pk_mul_f32 v[26:27], v[26:27], v[130:131] op_sel_hi:[1,0]
	v_pk_mul_f32 v[24:25], v[24:25], v[130:131] op_sel_hi:[1,0]
	v_pk_mul_f32 v[22:23], v[22:23], v[130:131] op_sel_hi:[1,0]
	v_pk_mul_f32 v[20:21], v[20:21], v[130:131] op_sel_hi:[1,0]
	v_pk_mul_f32 v[18:19], v[18:19], v[130:131] op_sel_hi:[1,0]
	v_pk_mul_f32 v[16:17], v[16:17], v[130:131] op_sel_hi:[1,0]
	s_branch .LBB0_462

; template <int MODE>
; __device__ __forceinline__ void nsa_compute(int cur, int buf, int t, int hl, u64 mymask, const bf16x8 (&Qf)[2][2], f32x4 (&O)[4][2], float (&m)[2], float (&l)[2],
;                                             const float (&inv)[2], float* impw, char* lds) {
;     ...
;       for (int kk = 0; kk < 2; ++kk)
; #pragma unroll
;         for (int e = 0; e < 4; ++e) {
;           const int off = 32 * s2 + 16 * kk + e;
;           int idx;
;           if (MODE <= 1) { idx = base - 16 * off; idx = idx > 0 ? idx : 0; } else idx = base - off;
;           sv[kk][e] = S[kk][r][e] * (0.125f * LOG2E) + tb[r * TS + idx];
;         }
;       float pv[2][4];
;       if (MODE == 1) {
; #pragma unroll
;         for (int kk = 0; kk < 2; ++kk)
; #pragma unroll
;           for (int e = 0; e < 4; ++e) pv[kk][e] = __builtin_amdgcn_exp2f(sv[kk][e] - m[r]) * inv[r];
; #pragma unroll
;         for (int kk = 0; kk < 2; ++kk) { g1s[kk] += pv[kk][0] + pv[kk][1] + pv[kk][2] + 0.5f * pv[kk][3]; p3s[kk] += 0.5f * pv[kk][3]; }
;       } else {
;         const float mxa = fmaxf(fmaxf(sv[0][0], sv[0][1]), sv[0][2]), mxb = fmaxf(fmaxf(sv[0][3], sv[1][0]), sv[1][1]);
;         float mx = fmaxf(fmaxf(fmaxf(sv[1][2], sv[1][3]), mxa), mxb);
;         if (MODE == 2) mx = selok ? mx : -__builtin_inff();
;         if (__any(mx > m[r] + 8.0f)) {
;           mx = fmaxf(mx, __shfl_xor(mx, 16)); mx = fmaxf(mx, __shfl_xor(mx, 32));
;           const float mn = fmaxf(m[r], mx), al = __builtin_amdgcn_exp2f(m[r] - mn);
;           m[r] = mn; l[r] *= al;
;           if (MODE != 0) {
; #pragma unroll
;             for (int df = 0; df < 4; ++df) O[df][r] *= al;
;           }
;         }
;         const float me = (MODE == 2) ? (selok ? m[r] : __builtin_inff()) : m[r];
;         float ps = 0.f;
; #pragma unroll
;         for (int kk = 0; kk < 2; ++kk)
; #pragma unroll
;           for (int e = 0; e < 4; ++e) { pv[kk][e] = __builtin_amdgcn_exp2f(sv[kk][e] - me); ps += pv[kk][e]; }
;         l[r] += ps;
.LBB0_462:
	v_cndmask_b32_e64 v129, v120, v228, s[36:37]
	v_sub_f32_e32 v115, v127, v129
	v_exp_f32_e32 v115, v115
	v_sub_f32_e32 v116, v116, v129
	v_exp_f32_e32 v116, v116
	v_sub_f32_e32 v117, v117, v129
	v_exp_f32_e32 v117, v117
	v_sub_f32_e32 v114, v114, v129
	v_exp_f32_e32 v114, v114
	v_add_f32_e32 v119, 0, v115
	v_add_f32_e32 v119, v116, v119
	v_add_f32_e32 v119, v117, v119
	v_sub_f32_e32 v113, v113, v129
	v_add_f32_e32 v120, v114, v119
	v_exp_f32_e32 v119, v113
	v_sub_f32_e32 v112, v112, v129
	v_add_f32_e32 v113, v119, v120
	v_exp_f32_e32 v120, v112
	s_nop 0
	v_add_f32_e32 v112, v120, v113
	v_sub_f32_e32 v113, v128, v129
	v_exp_f32_e32 v121, v113
	v_sub_f32_e32 v113, v118, v129
	v_exp_f32_e32 v118, v113
	v_add_f32_e32 v112, v121, v112
	v_add_f32_e32 v112, v118, v112
	v_add_f32_e32 v146, v146, v112
	s_waitcnt lgkmcnt(3)
	v_fmamk_f32 v113, v108, 0x3e38aa3b, v171
	v_fmamk_f32 v112, v109, 0x3e38aa3b, v170
	s_waitcnt lgkmcnt(2)
	v_fmamk_f32 v109, v110, 0x3e38aa3b, v173
	v_fmamk_f32 v108, v111, 0x3e38aa3b, v172
	s_waitcnt lgkmcnt(1)
	v_fmamk_f32 v111, v104, 0x3e38aa3b, v175
	v_fmamk_f32 v110, v105, 0x3e38aa3b, v174
	s_waitcnt lgkmcnt(0)
	v_fmamk_f32 v105, v106, 0x3e38aa3b, v193
	v_fmamk_f32 v104, v107, 0x3e38aa3b, v192
	v_max3_f32 v106, v113, v112, v109
	v_max3_f32 v107, v108, v111, v110
	v_max_f32_e32 v122, v105, v104
	v_max3_f32 v106, v122, v106, v107
	v_cndmask_b32_e64 v106, v106, v225, s[36:37]
	v_add_f32_e32 v107, 0x41000000, v189
	v_cmp_gt_f32_e32 vcc, v106, v107
	s_cbranch_vccz .LBB0_464
	ds_bpermute_b32 v107, v233, v106
	v_max_f32_e32 v106, v106, v106
	s_waitcnt lgkmcnt(0)
	v_max_f32_e32 v107, v107, v107
	v_max_f32_e32 v106, v106, v107
	ds_bpermute_b32 v107, v234, v106
	s_waitcnt lgkmcnt(0)
	v_max3_f32 v106, v189, v106, v107
	v_sub_f32_e32 v107, v189, v106
	v_exp_f32_e32 v122, v107
	v_mov_b32_e32 v189, v106
	v_mul_f32_e32 v147, v147, v122
	v_pk_mul_f32 v[46:47], v[46:47], v[122:123] op_sel_hi:[1,0]
	v_pk_mul_f32 v[44:45], v[44:45], v[122:123] op_sel_hi:[1,0]
	v_pk_mul_f32 v[42:43], v[42:43], v[122:123] op_sel_hi:[1,0]
	v_pk_mul_f32 v[40:41], v[40:41], v[122:123] op_sel_hi:[1,0]
	v_pk_mul_f32 v[38:39], v[38:39], v[122:123] op_sel_hi:[1,0]
	v_pk_mul_f32 v[36:37], v[36:37], v[122:123] op_sel_hi:[1,0]
	v_pk_mul_f32 v[34:35], v[34:35], v[122:123] op_sel_hi:[1,0]
	v_pk_mul_f32 v[32:33], v[32:33], v[122:123] op_sel_hi:[1,0]
	s_branch .LBB0_465

; template <int MODE>
; __device__ __forceinline__ void nsa_compute(int cur, int buf, int t, int hl, u64 mymask, const bf16x8 (&Qf)[2][2], f32x4 (&O)[4][2], float (&m)[2], float (&l)[2],
;                                             const float (&inv)[2], float* impw, char* lds) {
;     ...
;   const bool selok = (MODE == 2) ? (((mymask >> cur) & 1ull) != 0ull) : true;
;   const float* tb = (MODE == 3) ? (const float*)(lds + NSA_TW) + hl * 640 : (const float*)(lds + NSA_T) + hl * 4160;
;   constexpr int TS = (MODE == 3) ? 640 : 4160;
;   const int base = (MODE <= 1) ? (t - 31 - 16 * (cur * 64 + 4 * fq) + 64) : (t - cur * 64 - 4 * fq + 64);
; #pragma unroll
;   for (int s2 = 0; s2 < 2; ++s2) {
;     f32x4 S[2][2] = {};
;     bf16x8 kfr[2][2];
; #pragma unroll
;     for (int ks = 0; ks < 2; ++ks)
; #pragma unroll
;       for (int kk = 0; kk < 2; ++kk) kfr[ks][kk] = *(const bf16x8*)(kt + (32 * s2 + 16 * kk + fr) * 128 + (((ks * 4 + fq) ^ (fr & 7)) << 4));
;     __builtin_amdgcn_s_setprio(1);
; #pragma unroll
;     for (int ks = 0; ks < 2; ++ks)
; #pragma unroll
;       for (int kk = 0; kk < 2; ++kk)
; #pragma unroll
;         for (int r = 0; r < 2; ++r) S[kk][r] = mfma16(kfr[ks][kk], Qf[r][ks], S[kk][r]);
;     __builtin_amdgcn_s_setprio(0);
;     bf16x8 Pf[2];
;     float g1s[2] = {0.f, 0.f}, p3s[2] = {0.f, 0.f};
; #pragma unroll
;     for (int r = 0; r < 2; ++r) {
;       float sv[2][4];
; #pragma unroll
;       for (int kk = 0; kk < 2; ++kk)
; #pragma unroll
;         for (int e = 0; e < 4; ++e) {
;           const int off = 32 * s2 + 16 * kk + e;
;           int idx;
;           if (MODE <= 1) { idx = base - 16 * off; idx = idx > 0 ? idx : 0; } else idx = base - off;
;           sv[kk][e] = S[kk][r][e] * (0.125f * LOG2E) + tb[r * TS + idx];
;         }
;       float pv[2][4];
;       if (MODE == 1) {
; #pragma unroll
;         for (int kk = 0; kk < 2; ++kk)
; #pragma unroll
;           for (int e = 0; e < 4; ++e) pv[kk][e] = __builtin_amdgcn_exp2f(sv[kk][e] - m[r]) * inv[r];
; #pragma unroll
;         for (int kk = 0; kk < 2; ++kk) { g1s[kk] += pv[kk][0] + pv[kk][1] + pv[kk][2] + 0.5f * pv[kk][3]; p3s[kk] += 0.5f * pv[kk][3]; }
;       } else {
;         const float mxa = fmaxf(fmaxf(sv[0][0], sv[0][1]), sv[0][2]), mxb = fmaxf(fmaxf(sv[0][3], sv[1][0]), sv[1][1]);
;         float mx = fmaxf(fmaxf(fmaxf(sv[1][2], sv[1][3]), mxa), mxb);
.LBB0_469:
	v_add_f32_e32 v16, 0, v136
	v_add_f32_e32 v16, v137, v16
	v_add_f32_e32 v16, v138, v16
	v_add_f32_e32 v16, v139, v16
	v_add_f32_e32 v16, v140, v16
	v_add_f32_e32 v16, v141, v16
	v_add_f32_e32 v16, v142, v16
	v_add_f32_e32 v16, v143, v16
	v_add_f32_e32 v147, v147, v16
	s_mov_b64 s[36:37], -1
	s_cmp_lt_i32 s62, 0
	s_mov_b64 vcc, -1
	s_cbranch_scc1 .LBB0_487
	s_lshl_b64 s[36:37], 1, s62
	v_mov_b32 v18, v179
	v_and_b32_e32 v17, s37, v187
	v_lshrrev_b32_e32 v19, 4, v18
	v_bfe_u32 v24, v18, 4, 2
	v_and_b32_e32 v16, s36, v186
	v_and_b32_e32 v25, 7, v18
	v_and_b32_e32 v150, 15, v18
	v_cmp_eq_u64_e64 s[36:37], 0, v[16:17]
	v_lshlrev_b32_e32 v151, 2, v24
	v_bitop3_b32 v16, v19, v25, 3 bitop3:0x6c
	v_bitop3_b32 v24, v24, v25, 4 bitop3:0x36
	v_lshlrev_b32_e32 v26, 7, v150
	v_lshl_add_u32 v16, v16, 4, s63
	v_lshl_add_u32 v24, v24, 4, s63
	v_add_u32_e32 v148, v16, v26
	v_add_u32_e32 v149, v24, v26
	ds_read_b128 v[16:19], v148
	ds_read_b128 v[20:23], v148 offset:2048
	ds_read_b128 v[24:27], v149
	ds_read_b128 v[32:35], v149 offset:2048
	v_sub_u32_e32 v251, v180, v151
	v_lshl_add_u32 v251, v251, 2, v181
	s_lshl_b32 s16, s62, 8
	v_subrev_u32_e32 v250, s16, v251
	v_add_u32_e32 v249, 0x8400, v250
	v_add_u32_e32 v248, 0xc500, v250
	ds_read2_b32 v[192:193], v249 offset0:63 offset1:64
	ds_read2_b32 v[194:195], v249 offset0:61 offset1:62
	ds_read2_b32 v[198:199], v249 offset0:47 offset1:48
	ds_read2_b32 v[200:201], v249 offset0:45 offset1:46
	ds_read2_b32 v[202:203], v248 offset0:63 offset1:64
	ds_read2_b32 v[204:205], v248 offset0:61 offset1:62
	ds_read2_b32 v[206:207], v248 offset0:47 offset1:48
	ds_read2_b32 v[208:209], v248 offset0:45 offset1:46
	s_setprio 1
	s_waitcnt lgkmcnt(11)
	v_mfma_f32_16x16x32_bf16 v[28:31], v[16:19], v[0:3], 0
	v_mfma_f32_16x16x32_bf16 v[16:19], v[16:19], v[8:11], 0
	s_waitcnt lgkmcnt(10)
	v_mfma_f32_16x16x32_bf16 v[36:39], v[20:23], v[0:3], 0
	v_mfma_f32_16x16x32_bf16 v[20:23], v[20:23], v[8:11], 0
	s_waitcnt lgkmcnt(9)
	v_mfma_f32_16x16x32_bf16 v[40:43], v[24:27], v[4:7], v[28:31]
	v_mfma_f32_16x16x32_bf16 v[28:31], v[24:27], v[12:15], v[16:19]
	s_waitcnt lgkmcnt(8)
	v_mfma_f32_16x16x32_bf16 v[16:19], v[32:35], v[4:7], v[36:39]
	v_mfma_f32_16x16x32_bf16 v[20:23], v[32:35], v[12:15], v[20:23]
	s_setprio 0
	v_sub_u32_e32 v24, v180, v151
	v_lshl_add_u32 v24, v24, 2, v181
	v_subrev_u32_e32 v158, s16, v24
	s_waitcnt lgkmcnt(7)
	v_fmamk_f32 v47, v40, 0x3e38aa3b, v193
	v_fmamk_f32 v46, v41, 0x3e38aa3b, v192
	s_waitcnt lgkmcnt(6)
	v_fmamk_f32 v39, v42, 0x3e38aa3b, v195
	v_fmamk_f32 v38, v43, 0x3e38aa3b, v194
	s_waitcnt lgkmcnt(5)
	v_fmamk_f32 v37, v16, 0x3e38aa3b, v199
	v_fmamk_f32 v36, v17, 0x3e38aa3b, v198
	v_max3_f32 v16, v47, v46, v39
	v_max3_f32 v17, v38, v37, v36
	s_waitcnt lgkmcnt(4)
	v_fmamk_f32 v45, v18, 0x3e38aa3b, v201
	v_fmamk_f32 v44, v19, 0x3e38aa3b, v200
	v_max_f32_e32 v18, v45, v44
	v_max3_f32 v16, v18, v16, v17
	v_cndmask_b32_e64 v16, v16, v225, s[36:37]
	v_add_f32_e32 v17, 0x41000000, v188
	v_cmp_gt_f32_e32 vcc, v16, v17
	s_cbranch_vccz .LBB0_472
	ds_bpermute_b32 v17, v233, v16
	v_max_f32_e32 v16, v16, v16
	v_mov_b32_e32 v137, v189
	v_mov_b32_e32 v191, v147
	s_waitcnt lgkmcnt(0)
	v_max_f32_e32 v17, v17, v17
	v_max_f32_e32 v16, v16, v17
	ds_bpermute_b32 v17, v234, v16
	s_waitcnt lgkmcnt(0)
	v_max3_f32 v136, v188, v16, v17
	v_sub_f32_e32 v16, v188, v136
	v_exp_f32_e32 v40, v16
	v_mov_b64_e32 v[188:189], v[136:137]
	v_mul_f32_e32 v190, v146, v40
	v_pk_mul_f32 v[18:19], v[106:107], v[40:41] op_sel_hi:[1,0]
	v_pk_mul_f32 v[16:17], v[104:105], v[40:41] op_sel_hi:[1,0]
	v_pk_mul_f32 v[26:27], v[126:127], v[40:41] op_sel_hi:[1,0]
	v_pk_mul_f32 v[24:25], v[124:125], v[40:41] op_sel_hi:[1,0]
	v_pk_mul_f32 v[34:35], v[130:131], v[40:41] op_sel_hi:[1,0]
	v_pk_mul_f32 v[32:33], v[128:129], v[40:41] op_sel_hi:[1,0]
	v_pk_mul_f32 v[42:43], v[134:135], v[40:41] op_sel_hi:[1,0]
	v_pk_mul_f32 v[40:41], v[132:133], v[40:41] op_sel_hi:[1,0]
	s_branch .LBB0_473

; template <int MODE>
; __device__ __forceinline__ void nsa_compute(int cur, int buf, int t, int hl, u64 mymask, const bf16x8 (&Qf)[2][2], f32x4 (&O)[4][2], float (&m)[2], float (&l)[2],
;                                             const float (&inv)[2], float* impw, char* lds) {
;     ...
;       for (int kk = 0; kk < 2; ++kk)
; #pragma unroll
;         for (int e = 0; e < 4; ++e) {
;           const int off = 32 * s2 + 16 * kk + e;
;           int idx;
;           if (MODE <= 1) { idx = base - 16 * off; idx = idx > 0 ? idx : 0; } else idx = base - off;
;           sv[kk][e] = S[kk][r][e] * (0.125f * LOG2E) + tb[r * TS + idx];
;         }
;       float pv[2][4];
;       if (MODE == 1) {
; #pragma unroll
;         for (int kk = 0; kk < 2; ++kk)
; #pragma unroll
;           for (int e = 0; e < 4; ++e) pv[kk][e] = __builtin_amdgcn_exp2f(sv[kk][e] - m[r]) * inv[r];
; #pragma unroll
;         for (int kk = 0; kk < 2; ++kk) { g1s[kk] += pv[kk][0] + pv[kk][1] + pv[kk][2] + 0.5f * pv[kk][3]; p3s[kk] += 0.5f * pv[kk][3]; }
;       } else {
;         const float mxa = fmaxf(fmaxf(sv[0][0], sv[0][1]), sv[0][2]), mxb = fmaxf(fmaxf(sv[0][3], sv[1][0]), sv[1][1]);
;         float mx = fmaxf(fmaxf(fmaxf(sv[1][2], sv[1][3]), mxa), mxb);
;         if (MODE == 2) mx = selok ? mx : -__builtin_inff();
;         if (__any(mx > m[r] + 8.0f)) {
;           mx = fmaxf(mx, __shfl_xor(mx, 16)); mx = fmaxf(mx, __shfl_xor(mx, 32));
;           const float mn = fmaxf(m[r], mx), al = __builtin_amdgcn_exp2f(m[r] - mn);
;           m[r] = mn; l[r] *= al;
;           if (MODE != 0) {
; #pragma unroll
;             for (int df = 0; df < 4; ++df) O[df][r] *= al;
;           }
;         }
;         const float me = (MODE == 2) ? (selok ? m[r] : __builtin_inff()) : m[r];
;         float ps = 0.f;
; #pragma unroll
;         for (int kk = 0; kk < 2; ++kk)
; #pragma unroll
;           for (int e = 0; e < 4; ++e) { pv[kk][e] = __builtin_amdgcn_exp2f(sv[kk][e] - me); ps += pv[kk][e]; }
;         l[r] += ps;
.LBB0_473:
	v_cndmask_b32_e64 v136, v136, v228, s[36:37]
	v_sub_f32_e32 v47, v47, v136
	v_exp_f32_e32 v152, v47
	v_sub_f32_e32 v46, v46, v136
	v_exp_f32_e32 v153, v46
	v_sub_f32_e32 v39, v39, v136
	v_exp_f32_e32 v154, v39
	v_sub_f32_e32 v38, v38, v136
	v_exp_f32_e32 v155, v38
	v_sub_f32_e32 v37, v37, v136
	v_add_f32_e32 v47, 0, v152
	v_exp_f32_e32 v156, v37
	v_sub_f32_e32 v36, v36, v136
	v_add_f32_e32 v46, v153, v47
	v_exp_f32_e32 v157, v36
	v_add_f32_e32 v39, v154, v46
	v_add_f32_e32 v38, v155, v39
	v_add_f32_e32 v37, v156, v38
	v_add_f32_e32 v36, v157, v37
	v_sub_f32_e32 v37, v45, v136
	v_exp_f32_e32 v159, v37
	v_sub_f32_e32 v37, v44, v136
	v_exp_f32_e32 v160, v37
	v_add_f32_e32 v36, v159, v36
	v_add_f32_e32 v36, v160, v36
	v_add_f32_e32 v190, v190, v36
	s_waitcnt lgkmcnt(3)
	v_fmamk_f32 v139, v28, 0x3e38aa3b, v203
	v_fmamk_f32 v138, v29, 0x3e38aa3b, v202
	s_waitcnt lgkmcnt(2)
	v_fmamk_f32 v141, v30, 0x3e38aa3b, v205
	v_fmamk_f32 v140, v31, 0x3e38aa3b, v204
	s_waitcnt lgkmcnt(1)
	v_fmamk_f32 v137, v20, 0x3e38aa3b, v207
	v_fmamk_f32 v136, v21, 0x3e38aa3b, v206
	v_max3_f32 v20, v139, v138, v141
	v_max3_f32 v21, v140, v137, v136
	s_waitcnt lgkmcnt(0)
	v_fmamk_f32 v143, v22, 0x3e38aa3b, v209
	v_fmamk_f32 v142, v23, 0x3e38aa3b, v208
	v_max_f32_e32 v22, v143, v142
	v_max3_f32 v20, v22, v20, v21
	v_cndmask_b32_e64 v20, v20, v225, s[36:37]
	v_add_f32_e32 v21, 0x41000000, v189
	v_cmp_gt_f32_e32 vcc, v20, v21
	s_cbranch_vccz .LBB0_475
	ds_bpermute_b32 v21, v233, v20
	v_max_f32_e32 v20, v20, v20
	s_waitcnt lgkmcnt(0)
	v_max_f32_e32 v21, v21, v21
	v_max_f32_e32 v20, v20, v21
	ds_bpermute_b32 v21, v234, v20
	s_waitcnt lgkmcnt(0)
	v_max3_f32 v161, v189, v20, v21
	v_sub_f32_e32 v20, v189, v161
	v_exp_f32_e32 v44, v20
	v_mov_b32_e32 v189, v161
	v_mul_f32_e32 v191, v191, v44
	v_pk_mul_f32 v[22:23], v[110:111], v[44:45] op_sel_hi:[1,0]
	v_pk_mul_f32 v[20:21], v[108:109], v[44:45] op_sel_hi:[1,0]
	v_pk_mul_f32 v[30:31], v[114:115], v[44:45] op_sel_hi:[1,0]
	v_pk_mul_f32 v[28:29], v[112:113], v[44:45] op_sel_hi:[1,0]
	v_pk_mul_f32 v[38:39], v[118:119], v[44:45] op_sel_hi:[1,0]
	v_pk_mul_f32 v[36:37], v[116:117], v[44:45] op_sel_hi:[1,0]
	v_pk_mul_f32 v[46:47], v[122:123], v[44:45] op_sel_hi:[1,0]
	v_pk_mul_f32 v[44:45], v[120:121], v[44:45] op_sel_hi:[1,0]
	s_branch .LBB0_476

; template <int MODE>
; __device__ __forceinline__ void nsa_compute(int cur, int buf, int t, int hl, u64 mymask, const bf16x8 (&Qf)[2][2], f32x4 (&O)[4][2], float (&m)[2], float (&l)[2],
;                                             const float (&inv)[2], float* impw, char* lds) {
;     ...
; #pragma unroll
;     for (int ks = 0; ks < 2; ++ks)
; #pragma unroll
;       for (int kk = 0; kk < 2; ++kk) kfr[ks][kk] = *(const bf16x8*)(kt + (32 * s2 + 16 * kk + fr) * 128 + (((ks * 4 + fq) ^ (fr & 7)) << 4));
;     __builtin_amdgcn_s_setprio(1);
; #pragma unroll
;     for (int ks = 0; ks < 2; ++ks)
; #pragma unroll
;       for (int kk = 0; kk < 2; ++kk)
; #pragma unroll
;         for (int r = 0; r < 2; ++r) S[kk][r] = mfma16(kfr[ks][kk], Qf[r][ks], S[kk][r]);
;     __builtin_amdgcn_s_setprio(0);
;     bf16x8 Pf[2];
;     float g1s[2] = {0.f, 0.f}, p3s[2] = {0.f, 0.f};
; #pragma unroll
;     for (int r = 0; r < 2; ++r) {
;       float sv[2][4];
; #pragma unroll
;       for (int kk = 0; kk < 2; ++kk)
; #pragma unroll
;         for (int e = 0; e < 4; ++e) {
;     ...
;         const float me = (MODE == 2) ? (selok ? m[r] : __builtin_inff()) : m[r];
;         float ps = 0.f;
; #pragma unroll
;         for (int kk = 0; kk < 2; ++kk)
; #pragma unroll
;           for (int e = 0; e < 4; ++e) { pv[kk][e] = __builtin_amdgcn_exp2f(sv[kk][e] - me); ps += pv[kk][e]; }
;         l[r] += ps;
;       }
;       if (MODE != 0) {
;         const unsigned w0 = pk2(pv[0][0], pv[0][1]), w1 = pk2(pv[0][2], pv[0][3]), w2 = pk2(pv[1][0], pv[1][1]), w3 = pk2(pv[1][2], pv[1][3]);
;         u32x4 pw; pw.x = w0; pw.y = w1; pw.z = w2; pw.w = w3;
;         Pf[r] = __builtin_bit_cast(bf16x8, pw);
;       }
;     }
;     if (MODE != 0) {
;       bf16x8 vfr[4];
; #pragma unroll
;       for (int df = 0; df < 4; ++df) {
;         const bf16x4 va = *(const bf16x4*)(vt + (df * 16 + fr) * 68 + 32 * s2 + 4 * fq);
;         const bf16x4 vb = *(const bf16x4*)(vt + (df * 16 + fr) * 68 + 32 * s2 + 16 + 4 * fq);
;         bf16x8 vf; vf[0] = va[0]; vf[1] = va[1]; vf[2] = va[2]; vf[3] = va[3]; vf[4] = vb[0]; vf[5] = vb[1]; vf[6] = vb[2]; vf[7] = vb[3];
;         vfr[df] = vf;
;       }
;       __builtin_amdgcn_s_setprio(1);
; #pragma unroll
;       for (int df = 0; df < 4; ++df)
; #pragma unroll
;         for (int r = 0; r < 2; ++r) O[df][r] = mfma16(vfr[df], Pf[r], O[df][r]);
;       __builtin_amdgcn_s_setprio(0);
.LBB0_476:
	v_cvt_pk_bf16_f32 v152, v152, v153
	v_cvt_pk_bf16_f32 v153, v154, v155
	v_cvt_pk_bf16_f32 v154, v156, v157
	v_cndmask_b32_e64 v156, v161, v228, s[36:37]
	v_sub_f32_e32 v139, v139, v156
	v_exp_f32_e32 v139, v139
	v_sub_f32_e32 v138, v138, v156
	v_exp_f32_e32 v138, v138
	v_sub_f32_e32 v141, v141, v156
	v_exp_f32_e32 v141, v141
	v_sub_f32_e32 v140, v140, v156
	v_exp_f32_e32 v140, v140
	v_sub_f32_e32 v137, v137, v156
	v_cvt_pk_bf16_f32 v155, v159, v160
	v_add_f32_e32 v157, 0, v139
	v_exp_f32_e32 v159, v137
	v_add_f32_e32 v157, v138, v157
	v_add_f32_e32 v157, v141, v157
	v_add_f32_e32 v157, v140, v157
	v_sub_f32_e32 v136, v136, v156
	v_add_f32_e32 v137, v159, v157
	v_exp_f32_e32 v157, v136
	s_nop 0
	v_add_f32_e32 v136, v157, v137
	v_sub_f32_e32 v137, v143, v156
	v_exp_f32_e32 v143, v137
	v_sub_f32_e32 v137, v142, v156
	v_exp_f32_e32 v142, v137
	v_cvt_pk_bf16_f32 v137, v141, v140
	v_mul_u32_u24_e32 v140, 0x44, v150
	v_add_f32_e32 v136, v143, v136
	v_lshlrev_b32_e32 v140, 1, v140
	v_lshlrev_b32_e32 v141, 1, v151
	v_add_f32_e32 v136, v142, v136
	v_add3_u32 v150, s71, v140, v141
	v_add_f32_e32 v191, v191, v136
	v_cvt_pk_bf16_f32 v136, v139, v138
	v_cvt_pk_bf16_f32 v138, v159, v157
	v_add_u32_e32 v159, 0x4000, v150
	v_add_u32_e32 v160, 0x4800, v150
	v_cvt_pk_bf16_f32 v139, v143, v142
	ds_read2_b64 v[140:143], v159 offset1:4
	ds_read2_b64 v[164:167], v160 offset0:16 offset1:20
	v_add_u32_e32 v161, 0x5000, v150
	v_add_u32_e32 v162, 0x5800, v150
	ds_read2_b64 v[168:171], v161 offset0:32 offset1:36
	ds_read2_b64 v[172:175], v162 offset0:48 offset1:52
	s_setprio 1
	s_waitcnt lgkmcnt(3)
	v_mfma_f32_16x16x32_bf16 v[16:19], v[140:143], v[152:155], v[16:19]
	v_mfma_f32_16x16x32_bf16 v[20:23], v[140:143], v[136:139], v[20:23]
	s_waitcnt lgkmcnt(2)
	v_mfma_f32_16x16x32_bf16 v[24:27], v[164:167], v[152:155], v[24:27]
	v_mfma_f32_16x16x32_bf16 v[28:31], v[164:167], v[136:139], v[28:31]
	s_waitcnt lgkmcnt(1)
	v_mfma_f32_16x16x32_bf16 v[32:35], v[168:171], v[152:155], v[32:35]
	v_mfma_f32_16x16x32_bf16 v[36:39], v[168:171], v[136:139], v[36:39]
	s_waitcnt lgkmcnt(0)
	v_mfma_f32_16x16x32_bf16 v[40:43], v[172:175], v[152:155], v[40:43]
	v_mfma_f32_16x16x32_bf16 v[44:47], v[172:175], v[136:139], v[44:47]
	s_setprio 0
	ds_read_b128 v[136:139], v148 offset:4096
	ds_read_b128 v[140:143], v148 offset:6144
	ds_read_b128 v[150:153], v149 offset:4096
	ds_read_b128 v[154:157], v149 offset:6144
	v_add_u32_e32 v251, 0x8400, v158
	v_add_u32_e32 v250, 0xc500, v158
	ds_read2_b32 v[192:193], v251 offset0:31 offset1:32
	ds_read2_b32 v[194:195], v251 offset0:29 offset1:30
	ds_read2_b32 v[198:199], v251 offset0:15 offset1:16
	ds_read2_b32 v[200:201], v251 offset0:13 offset1:14
	ds_read2_b32 v[202:203], v250 offset0:31 offset1:32
	ds_read2_b32 v[204:205], v250 offset0:29 offset1:30
	ds_read2_b32 v[206:207], v250 offset0:15 offset1:16
	ds_read2_b32 v[208:209], v250 offset0:13 offset1:14
	s_setprio 1
	s_waitcnt lgkmcnt(11)
	v_mfma_f32_16x16x32_bf16 v[164:167], v[136:139], v[0:3], 0
	v_mfma_f32_16x16x32_bf16 v[136:139], v[136:139], v[8:11], 0
	s_waitcnt lgkmcnt(10)
	v_mfma_f32_16x16x32_bf16 v[172:175], v[140:143], v[8:11], 0
	v_mfma_f32_16x16x32_bf16 v[168:171], v[140:143], v[0:3], 0
	s_waitcnt lgkmcnt(9)
	v_mfma_f32_16x16x32_bf16 v[164:167], v[150:153], v[4:7], v[164:167]
	v_mfma_f32_16x16x32_bf16 v[140:143], v[150:153], v[12:15], v[136:139]
	s_waitcnt lgkmcnt(8)
	v_mfma_f32_16x16x32_bf16 v[136:139], v[154:157], v[12:15], v[172:175]
	v_mfma_f32_16x16x32_bf16 v[168:171], v[154:157], v[4:7], v[168:171]
	s_setprio 0
	s_waitcnt lgkmcnt(7)
	s_nop 1
	v_fmamk_f32 v163, v164, 0x3e38aa3b, v193
	v_fmamk_f32 v152, v165, 0x3e38aa3b, v192
	s_waitcnt lgkmcnt(6)
	v_fmamk_f32 v153, v166, 0x3e38aa3b, v195
	v_fmamk_f32 v150, v167, 0x3e38aa3b, v194
	s_waitcnt lgkmcnt(5)
	v_fmamk_f32 v149, v168, 0x3e38aa3b, v199
	v_fmamk_f32 v148, v169, 0x3e38aa3b, v198
	v_max3_f32 v151, v163, v152, v153
	s_waitcnt lgkmcnt(4)
	v_fmamk_f32 v164, v170, 0x3e38aa3b, v201
	v_fmamk_f32 v154, v171, 0x3e38aa3b, v200
	v_max3_f32 v155, v150, v149, v148
	v_max_f32_e32 v156, v164, v154
	v_max3_f32 v151, v156, v151, v155
	v_cndmask_b32_e64 v151, v151, v225, s[36:37]
	v_add_f32_e32 v155, 0x41000000, v188
	v_cmp_gt_f32_e32 vcc, v151, v155
	s_cbranch_vccz .LBB0_478
	ds_bpermute_b32 v155, v233, v151
	v_max_f32_e32 v151, v151, v151
	v_mov_b32_e32 v157, v189
	s_waitcnt lgkmcnt(0)
	v_max_f32_e32 v155, v155, v155
	v_max_f32_e32 v151, v151, v155
	ds_bpermute_b32 v155, v234, v151
	s_waitcnt lgkmcnt(0)
	v_max3_f32 v156, v188, v151, v155
	v_sub_f32_e32 v151, v188, v156
	v_exp_f32_e32 v166, v151
	v_mov_b64_e32 v[188:189], v[156:157]
	v_mul_f32_e32 v190, v190, v166
	v_pk_mul_f32 v[18:19], v[18:19], v[166:167] op_sel_hi:[1,0]
	v_pk_mul_f32 v[16:17], v[16:17], v[166:167] op_sel_hi:[1,0]
	v_pk_mul_f32 v[26:27], v[26:27], v[166:167] op_sel_hi:[1,0]
	v_pk_mul_f32 v[24:25], v[24:25], v[166:167] op_sel_hi:[1,0]
	v_pk_mul_f32 v[34:35], v[34:35], v[166:167] op_sel_hi:[1,0]
	v_pk_mul_f32 v[32:33], v[32:33], v[166:167] op_sel_hi:[1,0]
	v_pk_mul_f32 v[42:43], v[42:43], v[166:167] op_sel_hi:[1,0]
	v_pk_mul_f32 v[40:41], v[40:41], v[166:167] op_sel_hi:[1,0]
	s_branch .LBB0_479

; template <int MODE>
; __device__ __forceinline__ void nsa_compute(int cur, int buf, int t, int hl, u64 mymask, const bf16x8 (&Qf)[2][2], f32x4 (&O)[4][2], float (&m)[2], float (&l)[2],
;                                             const float (&inv)[2], float* impw, char* lds) {
;     ...
;       for (int kk = 0; kk < 2; ++kk)
; #pragma unroll
;         for (int e = 0; e < 4; ++e) {
;           const int off = 32 * s2 + 16 * kk + e;
;           int idx;
;           if (MODE <= 1) { idx = base - 16 * off; idx = idx > 0 ? idx : 0; } else idx = base - off;
;           sv[kk][e] = S[kk][r][e] * (0.125f * LOG2E) + tb[r * TS + idx];
;         }
;       float pv[2][4];
;       if (MODE == 1) {
; #pragma unroll
;         for (int kk = 0; kk < 2; ++kk)
; #pragma unroll
;           for (int e = 0; e < 4; ++e) pv[kk][e] = __builtin_amdgcn_exp2f(sv[kk][e] - m[r]) * inv[r];
; #pragma unroll
;         for (int kk = 0; kk < 2; ++kk) { g1s[kk] += pv[kk][0] + pv[kk][1] + pv[kk][2] + 0.5f * pv[kk][3]; p3s[kk] += 0.5f * pv[kk][3]; }
;       } else {
;         const float mxa = fmaxf(fmaxf(sv[0][0], sv[0][1]), sv[0][2]), mxb = fmaxf(fmaxf(sv[0][3], sv[1][0]), sv[1][1]);
;         float mx = fmaxf(fmaxf(fmaxf(sv[1][2], sv[1][3]), mxa), mxb);
;         if (MODE == 2) mx = selok ? mx : -__builtin_inff();
;         if (__any(mx > m[r] + 8.0f)) {
;           mx = fmaxf(mx, __shfl_xor(mx, 16)); mx = fmaxf(mx, __shfl_xor(mx, 32));
;           const float mn = fmaxf(m[r], mx), al = __builtin_amdgcn_exp2f(m[r] - mn);
;           m[r] = mn; l[r] *= al;
;           if (MODE != 0) {
; #pragma unroll
;             for (int df = 0; df < 4; ++df) O[df][r] *= al;
;           }
;         }
;         const float me = (MODE == 2) ? (selok ? m[r] : __builtin_inff()) : m[r];
;         float ps = 0.f;
; #pragma unroll
;         for (int kk = 0; kk < 2; ++kk)
; #pragma unroll
;           for (int e = 0; e < 4; ++e) { pv[kk][e] = __builtin_amdgcn_exp2f(sv[kk][e] - me); ps += pv[kk][e]; }
;         l[r] += ps;
.LBB0_479:
	v_cndmask_b32_e64 v165, v156, v228, s[36:37]
	v_sub_f32_e32 v151, v163, v165
	v_exp_f32_e32 v151, v151
	v_sub_f32_e32 v152, v152, v165
	v_exp_f32_e32 v152, v152
	v_sub_f32_e32 v153, v153, v165
	v_exp_f32_e32 v153, v153
	v_sub_f32_e32 v150, v150, v165
	v_exp_f32_e32 v150, v150
	v_add_f32_e32 v155, 0, v151
	v_add_f32_e32 v155, v152, v155
	v_add_f32_e32 v155, v153, v155
	v_sub_f32_e32 v149, v149, v165
	v_add_f32_e32 v156, v150, v155
	v_exp_f32_e32 v155, v149
	v_sub_f32_e32 v148, v148, v165
	v_add_f32_e32 v149, v155, v156
	v_exp_f32_e32 v156, v148
	s_nop 0
	v_add_f32_e32 v148, v156, v149
	v_sub_f32_e32 v149, v164, v165
	v_exp_f32_e32 v157, v149
	v_sub_f32_e32 v149, v154, v165
	v_exp_f32_e32 v154, v149
	v_add_f32_e32 v148, v157, v148
	v_add_f32_e32 v148, v154, v148
	v_add_f32_e32 v190, v190, v148
	s_waitcnt lgkmcnt(3)
	v_fmamk_f32 v149, v140, 0x3e38aa3b, v203
	v_fmamk_f32 v148, v141, 0x3e38aa3b, v202
	s_waitcnt lgkmcnt(2)
	v_fmamk_f32 v141, v142, 0x3e38aa3b, v205
	v_fmamk_f32 v140, v143, 0x3e38aa3b, v204
	s_waitcnt lgkmcnt(1)
	v_fmamk_f32 v143, v136, 0x3e38aa3b, v207
	v_fmamk_f32 v142, v137, 0x3e38aa3b, v206
	s_waitcnt lgkmcnt(0)
	v_fmamk_f32 v158, v138, 0x3e38aa3b, v209
	v_fmamk_f32 v136, v139, 0x3e38aa3b, v208
	v_max3_f32 v137, v149, v148, v141
	v_max3_f32 v138, v140, v143, v142
	v_max_f32_e32 v139, v158, v136
	v_max3_f32 v137, v139, v137, v138
	v_cndmask_b32_e64 v137, v137, v225, s[36:37]
	v_add_f32_e32 v138, 0x41000000, v189
	v_cmp_gt_f32_e32 vcc, v137, v138
	s_cbranch_vccz .LBB0_481
	ds_bpermute_b32 v138, v233, v137
	v_max_f32_e32 v137, v137, v137
	s_waitcnt lgkmcnt(0)
	v_max_f32_e32 v138, v138, v138
	v_max_f32_e32 v137, v137, v138
	ds_bpermute_b32 v138, v234, v137
	s_waitcnt lgkmcnt(0)
	v_max3_f32 v137, v189, v137, v138
	v_sub_f32_e32 v138, v189, v137
	v_exp_f32_e32 v138, v138
	v_mov_b32_e32 v189, v137
	v_mul_f32_e32 v191, v191, v138
	v_pk_mul_f32 v[22:23], v[22:23], v[138:139] op_sel_hi:[1,0]
	v_pk_mul_f32 v[20:21], v[20:21], v[138:139] op_sel_hi:[1,0]
	v_pk_mul_f32 v[30:31], v[30:31], v[138:139] op_sel_hi:[1,0]
	v_pk_mul_f32 v[28:29], v[28:29], v[138:139] op_sel_hi:[1,0]
	v_pk_mul_f32 v[38:39], v[38:39], v[138:139] op_sel_hi:[1,0]
	v_pk_mul_f32 v[36:37], v[36:37], v[138:139] op_sel_hi:[1,0]
	v_pk_mul_f32 v[46:47], v[46:47], v[138:139] op_sel_hi:[1,0]
	v_pk_mul_f32 v[44:45], v[44:45], v[138:139] op_sel_hi:[1,0]
	s_branch .LBB0_482
